# out-projection epilogue residual loads waited with a counted ladder; prompt-unit closing barrier waits vmcnt(6) so the 6 epilogue preloads stay in flight until their first use
# speedup vs baseline: 1.0072x; 1.0072x over previous
; #define ATT_WAIT_BAR() asm volatile("s_waitcnt vmcnt(0) lgkmcnt(0)\n\ts_barrier" ::: "memory")
; template <int TYPE>
; __device__ __forceinline__ void epi_preload(EpiPre& e, const Args& a, int l, int h, size_t rowq, int col, int lane) {
;     const int ch = lane & 7;
;     const float* gp = (TYPE == 0 ? a.gn_a : a.gn_b) + (size_t)l * W + h * HD + ch * 8;
;     e.g0 = *(const f32x4*)gp; e.g1 = *(const f32x4*)(gp + 4);
; #pragma unroll
;     for (int i = 0; i < 4; ++i) e.z[i] = *(const u32x4*)((const bf16*)(a.ws + WS_Z) + (rowq + i * 8 + (lane >> 3)) * D + col + ch * 8);
; }
; __device__ __forceinline__ void prompt_unit_sb(const Args& a, int l, int b, int h, int qb, LAS unsigned char* lds) {
;     ...
;     EpiPre pre; epi_preload<1>(pre, a, l, h, rowb + q0 + wid * 32, col, lane);
;     ATT_WAIT_BAR();
.LBB0_300:
	v_readlane_b32 s4, v242, 28
	v_readlane_b32 s5, v242, 29
	s_mov_b32 s1, s87
	v_lshlrev_b32_e32 v4, 1, v168
	v_lshl_add_u64 v[2:3], s[4:5], 0, v[166:167]
	v_lshl_add_u64 v[2:3], v[2:3], 0, s[0:1]
	v_lshl_add_u64 v[2:3], v[2:3], 0, v[4:5]
	global_load_dwordx4 v[60:63], v[2:3], off offset:1024
	v_readlane_b32 s4, v242, 12
	v_readlane_b32 s6, v242, 14
	v_readlane_b32 s5, v242, 13
	v_readlane_b32 s7, v242, 15
	s_add_u32 s4, s6, s92
	v_lshlrev_b32_e32 v3, 2, v168
	s_addc_u32 s5, s7, 0
	v_readlane_b32 s6, v242, 30
	global_load_dwordx4 v[14:17], v3, s[4:5]
	v_readlane_b32 s7, v242, 31
	s_lshl_b32 s3, s82, 13
	v_lshlrev_b32_e32 v68, 2, v169
	v_lshl_add_u64 v[6:7], s[6:7], 0, v[166:167]
	v_readlane_b32 s6, v242, 32
	v_readlane_b32 s7, v242, 33
	s_add_i32 s3, s3, 0
	v_readlane_b32 s10, v242, 36
	v_lshl_add_u64 v[8:9], s[6:7], 0, v[166:167]
	v_readlane_b32 s6, v242, 34
	v_readlane_b32 s7, v242, 35
	v_lshl_add_u64 v[6:7], v[6:7], 0, s[0:1]
	v_lshl_add_u64 v[8:9], v[8:9], 0, s[0:1]
	v_lshl_add_u64 v[10:11], s[6:7], 0, v[166:167]
	v_lshl_add_u64 v[52:53], v[10:11], 0, s[0:1]
	global_load_dwordx4 v[10:13], v3, s[4:5] offset:16
	v_add3_u32 v3, s3, v171, v68
	v_and_b32_e32 v2, 7, v19
	v_readlane_b32 s11, v242, 37
	v_lshl_add_u64 v[6:7], v[6:7], 0, v[4:5]
	v_lshl_add_u64 v[8:9], v[8:9], 0, v[4:5]
	v_lshl_add_u64 v[66:67], v[52:53], 0, v[4:5]
	v_add_u32_e32 v4, 0x800, v3
	v_lshl_add_u64 v[64:65], s[10:11], 0, v[166:167]
	global_load_dwordx4 v[56:59], v[6:7], off offset:1024
	global_load_dwordx4 v[52:55], v[8:9], off offset:1024
	s_nop 0
	global_load_dwordx4 v[6:9], v[66:67], off offset:1024
	s_waitcnt vmcnt(6) lgkmcnt(0)
	s_barrier
; #define LAS __attribute__((address_space(3)))
; __device__ __forceinline__ float bflo(unsigned w) { return __uint_as_float(w << 16); }
; __device__ __forceinline__ float bfhi(unsigned w) { return __uint_as_float(w & 0xffff0000u); }
; __device__ __forceinline__ int crow(int r, int hi) { return (r & 3) + 8 * (r >> 2) + 4 * hi; }
; __device__ __forceinline__ unsigned cvtpk(float lo, float hi) { f32x2 v = {lo, hi}; bf16x2_t b = __builtin_convertvector(v, bf16x2_t); return __builtin_bit_cast(unsigned, b); }
; #define ATT_LDS_WAIT() asm volatile("s_waitcnt lgkmcnt(0)" ::: "memory")
; __device__ __forceinline__ float gate8(const f32x4& x0, const f32x4& x1, const float (&gn)[8], const u32x4& zw, bf16* orow) {
;     const float zz[8] = {bflo(zw.x), bfhi(zw.x), bflo(zw.y), bfhi(zw.y), bflo(zw.z), bfhi(zw.z), bflo(zw.w), bfhi(zw.w)};
;     const float xs[8] = {x0[0], x0[1], x0[2], x0[3], x1[0], x1[1], x1[2], x1[3]};
;     float r[8], ssq = 0.f;
; #pragma unroll
;     for (int i = 0; i < 8; ++i) { ssq += xs[i] * xs[i]; r[i] = xs[i] * gn[i] * (zz[i] / (1.0f + __expf(-zz[i]))); }
;     u32x4 w; w.x = cvtpk(r[0], r[1]); w.y = cvtpk(r[2], r[3]); w.z = cvtpk(r[4], r[5]); w.w = cvtpk(r[6], r[7]);
;     *(u32x4*)orow = w;
;     return ssq;
; }
; template <int TYPE>
; __device__ __forceinline__ void prompt_epilogue(const Args& a, int l, int h, size_t rowq  , int col, FoxState& st, const EpiPre& pre, LAS float* wsf, LAS float* stg, int lane, int r32, int hi) {
;     ...
; #pragma unroll
;     for (int r = 0; r < 16; ++r) { stg[crow(r, hi) * 64 + r32] = st.o[0][r]; stg[crow(r, hi) * 64 + 32 + r32] = st.o[1][r]; }
;     ATT_LDS_WAIT();
;     const int ch = lane & 7;
;     const float gn[8] = {pre.g0[0], pre.g0[1], pre.g0[2], pre.g0[3], pre.g1[0], pre.g1[1], pre.g1[2], pre.g1[3]};
; #pragma unroll
;     for (int i = 0; i < 4; ++i) {
;         const int row = i * 8 + (lane >> 3); const size_t grow = rowq + row;
;         const f32x4 x0 = *(const LAS f32x4*)(stg + row * 64 + ch * 8), x1 = *(const LAS f32x4*)(stg + row * 64 + ch * 8 + 4);
;         float ssq = gate8(x0, x1, gn, pre.z[i], (bf16*)(a.ws + WS_HN) + grow * D + col + ch * 8);
;         ssq = sum8_dpp(ssq);
;         if (ch == 0) ((float*)(a.ws + WS_SSQ))[grow * 16 + TYPE * 8 + h] = ssq;
;     }
	v_lshl_add_u32 v19, v2, 5, s3
	ds_write2_b32 v3, v20, v36 offset1:32
	ds_write2_b32 v3, v21, v37 offset0:64 offset1:96
	ds_write2_b32 v3, v22, v38 offset0:128 offset1:160
	ds_write2_b32 v3, v23, v39 offset0:192 offset1:224
	v_add_u32_e32 v20, 0x1000, v3
	v_add_u32_e32 v3, 0x1800, v3
	ds_write2_b32 v4, v24, v40 offset1:32
	ds_write2_b32 v4, v25, v41 offset0:64 offset1:96
	ds_write2_b32 v4, v26, v42 offset0:128 offset1:160
	ds_write2_b32 v4, v27, v43 offset0:192 offset1:224
	ds_write2_b32 v20, v28, v44 offset1:32
	ds_write2_b32 v20, v29, v45 offset0:64 offset1:96
	ds_write2_b32 v20, v30, v46 offset0:128 offset1:160
	ds_write2_b32 v20, v31, v47 offset0:192 offset1:224
	ds_write2_b32 v3, v32, v48 offset1:32
	ds_write2_b32 v3, v33, v49 offset0:64 offset1:96
	ds_write2_b32 v3, v34, v50 offset0:128 offset1:160
	ds_write2_b32 v3, v35, v51 offset0:192 offset1:224
	v_lshl_add_u32 v36, v1, 8, v19
	s_waitcnt lgkmcnt(0)
	v_lshl_add_u64 v[24:25], v[64:65], 0, s[0:1]
	v_lshlrev_b32_e32 v4, 4, v2
	ds_read_b128 v[20:23], v36
	v_lshl_add_u64 v[28:29], v[24:25], 0, v[4:5]
	ds_read_b128 v[24:27], v36 offset:16
	v_cmp_eq_u32_e64 s[6:7], 0, v2
	s_waitcnt lgkmcnt(1)
	v_mul_f32_e32 v3, v21, v21
	v_fmac_f32_e32 v3, v20, v20
	v_fmac_f32_e32 v3, v22, v22
	v_fmac_f32_e32 v3, v23, v23
	s_waitcnt lgkmcnt(0)
	v_fmac_f32_e32 v3, v24, v24
	v_fmac_f32_e32 v3, v25, v25
	v_fmac_f32_e32 v3, v26, v26
	v_fmac_f32_e32 v3, v27, v27
	s_waitcnt vmcnt(5)
	s_waitcnt vmcnt(0)
	v_lshlrev_b32_e32 v4, 16, v60
	v_and_b32_e32 v36, 0xffff0000, v60
	v_mul_f32_e32 v30, 0xbfb8aa3b, v4
	v_mul_f32_e32 v31, 0xbfb8aa3b, v36
	v_exp_f32_e32 v30, v30
	v_exp_f32_e32 v31, v31
	v_lshlrev_b32_e32 v37, 16, v61
	v_and_b32_e32 v38, 0xffff0000, v61
	v_mul_f32_e32 v32, 0xbfb8aa3b, v37
	v_pk_add_f32 v[30:31], v[30:31], 1.0 op_sel_hi:[1,0]
	v_mul_f32_e32 v33, 0xbfb8aa3b, v38
	v_div_scale_f32 v39, s[4:5], v31, v31, v36
	v_div_scale_f32 v41, s[4:5], v30, v30, v4
	v_rcp_f32_e32 v42, v39
	v_rcp_f32_e32 v43, v41
	v_div_scale_f32 v40, vcc, v36, v31, v36
	v_fma_f32 v45, -v39, v42, 1.0
	v_fma_f32 v46, -v41, v43, 1.0
	v_fmac_f32_e32 v42, v45, v42
	v_div_scale_f32 v44, s[8:9], v4, v30, v4
	v_fmac_f32_e32 v43, v46, v43
	v_mul_f32_e32 v45, v40, v42
	v_exp_f32_e32 v32, v32
	v_exp_f32_e32 v33, v33
	v_mul_f32_e32 v46, v44, v43
	v_fma_f32 v47, -v39, v45, v40
	v_fma_f32 v48, -v41, v46, v44
	v_fmac_f32_e32 v45, v47, v42
	v_fmac_f32_e32 v46, v48, v43
	v_fma_f32 v39, -v39, v45, v40
	v_fma_f32 v40, -v41, v46, v44
	v_div_fmas_f32 v39, v39, v42, v45
	s_mov_b64 vcc, s[8:9]
	v_pk_add_f32 v[32:33], v[32:33], 1.0 op_sel_hi:[1,0]
	v_div_fixup_f32 v31, v39, v31, v36
	v_div_fmas_f32 v36, v40, v43, v46
	v_div_fixup_f32 v30, v36, v30, v4
	v_div_scale_f32 v4, s[4:5], v33, v33, v38
	v_rcp_f32_e32 v36, v4
	s_waitcnt vmcnt(4)
	v_pk_mul_f32 v[34:35], v[16:17], v[22:23]
	v_pk_mul_f32 v[20:21], v[14:15], v[20:21]
	v_and_b32_e32 v40, 0xffff0000, v63
	v_fma_f32 v22, -v4, v36, 1.0
	v_fmac_f32_e32 v36, v22, v36
	v_div_scale_f32 v22, vcc, v38, v33, v38
	v_mul_f32_e32 v23, v22, v36
	v_pk_mul_f32 v[20:21], v[30:31], v[20:21]
	v_fma_f32 v30, -v4, v23, v22
	v_fmac_f32_e32 v23, v30, v36
	v_fma_f32 v4, -v4, v23, v22
	v_div_scale_f32 v22, s[4:5], v32, v32, v37
	v_rcp_f32_e32 v30, v22
	v_div_fmas_f32 v4, v4, v36, v23
	v_div_fixup_f32 v23, v4, v33, v38
	v_lshlrev_b32_e32 v36, 16, v62
	v_fma_f32 v4, -v22, v30, 1.0
	v_fmac_f32_e32 v30, v4, v30
	v_div_scale_f32 v4, vcc, v37, v32, v37
	v_mul_f32_e32 v31, v4, v30
	v_fma_f32 v33, -v22, v31, v4
	v_fmac_f32_e32 v31, v33, v30
	v_fma_f32 v4, -v22, v31, v4
	v_and_b32_e32 v38, 0xffff0000, v62
	v_mul_f32_e32 v22, 0xbfb8aa3b, v36
	v_div_fmas_f32 v4, v4, v30, v31
	v_exp_f32_e32 v30, v22
	v_mul_f32_e32 v22, 0xbfb8aa3b, v38
	v_exp_f32_e32 v31, v22
	v_div_fixup_f32 v22, v4, v32, v37
	v_pk_mul_f32 v[22:23], v[22:23], v[34:35]
	s_waitcnt vmcnt(3)
	v_pk_mul_f32 v[32:33], v[12:13], v[26:27]
	v_pk_add_f32 v[30:31], v[30:31], 1.0 op_sel_hi:[1,0]
	v_pk_mul_f32 v[24:25], v[10:11], v[24:25]
	v_div_scale_f32 v4, s[4:5], v31, v31, v38
	v_rcp_f32_e32 v34, v4
	v_add_f32_dpp v3, v3, v3 quad_perm:[1,0,3,2] row_mask:0xf bank_mask:0xf bound_ctrl:1
	v_cvt_pk_bf16_f32 v20, v20, v21
	v_cvt_pk_bf16_f32 v21, v22, v23
	v_fma_f32 v35, -v4, v34, 1.0
	v_fmac_f32_e32 v34, v35, v34
	v_div_scale_f32 v35, vcc, v38, v31, v38
	v_mul_f32_e32 v37, v35, v34
	v_fma_f32 v39, -v4, v37, v35
	v_fmac_f32_e32 v37, v39, v34
	v_fma_f32 v4, -v4, v37, v35
	v_div_scale_f32 v35, s[4:5], v30, v30, v36
	v_rcp_f32_e32 v39, v35
	v_div_fmas_f32 v4, v4, v34, v37
	v_div_fixup_f32 v31, v4, v31, v38
	v_lshlrev_b32_e32 v38, 16, v63
	v_fma_f32 v4, -v35, v39, 1.0
	v_fmac_f32_e32 v39, v4, v39
	v_div_scale_f32 v4, vcc, v36, v30, v36
	v_mul_f32_e32 v37, v4, v39
	v_fma_f32 v34, -v35, v37, v4
	v_fmac_f32_e32 v37, v34, v39
	v_fma_f32 v4, -v35, v37, v4
	v_mul_f32_e32 v34, 0xbfb8aa3b, v38
	v_mul_f32_e32 v35, 0xbfb8aa3b, v40
	v_exp_f32_e32 v34, v34
	v_exp_f32_e32 v35, v35
	v_div_fmas_f32 v4, v4, v39, v37
	v_div_fixup_f32 v30, v4, v30, v36
	v_pk_mul_f32 v[24:25], v[30:31], v[24:25]
	v_pk_add_f32 v[34:35], v[34:35], 1.0 op_sel_hi:[1,0]
	v_add_f32_dpp v3, v3, v3 quad_perm:[2,3,0,1] row_mask:0xf bank_mask:0xf bound_ctrl:1
	v_div_scale_f32 v4, s[4:5], v35, v35, v40
	v_rcp_f32_e32 v36, v4
	v_cvt_pk_bf16_f32 v22, v24, v25
	v_fma_f32 v26, -v4, v36, 1.0
	v_fmac_f32_e32 v36, v26, v36
	v_div_scale_f32 v26, vcc, v40, v35, v40
	v_mul_f32_e32 v27, v26, v36
	v_fma_f32 v30, -v4, v27, v26
	v_fmac_f32_e32 v27, v30, v36
	v_fma_f32 v4, -v4, v27, v26
	v_div_scale_f32 v26, s[4:5], v34, v34, v38
	v_rcp_f32_e32 v30, v26
	v_div_fmas_f32 v4, v4, v36, v27
	v_div_fixup_f32 v27, v4, v35, v40
	v_fma_f32 v4, -v26, v30, 1.0
	v_fmac_f32_e32 v30, v4, v30
	v_div_scale_f32 v4, vcc, v38, v34, v38
	v_mul_f32_e32 v31, v4, v30
	v_fma_f32 v35, -v26, v31, v4
	v_fmac_f32_e32 v31, v35, v30
	v_fma_f32 v4, -v26, v31, v4
	v_div_fmas_f32 v4, v4, v30, v31
	v_div_fixup_f32 v26, v4, v34, v38
	v_pk_mul_f32 v[26:27], v[26:27], v[32:33]
	v_mov_b32_e32 v4, v5
	v_cvt_pk_bf16_f32 v23, v26, v27
	global_store_dwordx4 v[28:29], v[20:23], off offset:1024
	v_mov_b32_dpp v4, v3 row_half_mirror row_mask:0xf bank_mask:0xf
	s_and_saveexec_b64 s[4:5], s[6:7]
	s_cbranch_execz .LBB0_302
	v_readlane_b32 s8, v242, 38
	v_lshlrev_b64 v[20:21], 6, v[160:161]
	v_readlane_b32 s9, v242, 39
	v_add_f32_e32 v3, v3, v4
	s_nop 0
	v_lshl_add_u64 v[20:21], s[8:9], 0, v[20:21]
	s_lshl_b32 s8, s77, 2
	s_mov_b32 s9, s87
	v_lshl_add_u64 v[20:21], v[20:21], 0, s[8:9]
	global_store_dword v[20:21], v3, off

; #define LAS __attribute__((address_space(3)))
; __device__ __forceinline__ int crow(int r, int hi) { return (r & 3) + 8 * (r >> 2) + 4 * hi; }
; __device__ __forceinline__ float swap_sum(float m) { auto rr = __builtin_amdgcn_permlane32_swap(__float_as_uint(m), __float_as_uint(m), false, false); return __uint_as_float(rr[0]) + __uint_as_float(rr[1]); }
; #define ATT_WAIT_BAR() asm volatile("s_waitcnt vmcnt(0) lgkmcnt(0)\n\ts_barrier" ::: "memory")
; #define ATT_LDS_WAIT() asm volatile("s_waitcnt lgkmcnt(0)" ::: "memory")
; template <int TYPE>
; __device__ __forceinline__ void prompt_epilogue(const Args& a, int l, int h, size_t rowq  , int col, FoxState& st, const EpiPre& pre, LAS float* wsf, LAS float* stg, int lane, int r32, int hi) {
;     if (TYPE == 0) {
;         const float inv = 1.0f / swap_sum(st.l);
;         if (hi == 0) wsf[r32] = inv;
;         ATT_LDS_WAIT();
; #pragma unroll
;         for (int g = 0; g < 4; ++g) { const f32x4 f = *(const LAS f32x4*)(wsf + 8 * g + 4 * hi);
; #pragma unroll
;             for (int i = 0; i < 4; ++i) { st.o[0][4 * g + i] *= f[i]; st.o[1][4 * g + i] *= f[i]; } }
;     }
; #pragma unroll
;     for (int r = 0; r < 16; ++r) { stg[crow(r, hi) * 64 + r32] = st.o[0][r]; stg[crow(r, hi) * 64 + 32 + r32] = st.o[1][r]; }
;     ATT_LDS_WAIT();
;     const int ch = lane & 7;
;     const float gn[8] = {pre.g0[0], pre.g0[1], pre.g0[2], pre.g0[3], pre.g1[0], pre.g1[1], pre.g1[2], pre.g1[3]};
; #pragma unroll
;     for (int i = 0; i < 4; ++i) {
;         const int row = i * 8 + (lane >> 3); const size_t grow = rowq + row;
;         const f32x4 x0 = *(const LAS f32x4*)(stg + row * 64 + ch * 8), x1 = *(const LAS f32x4*)(stg + row * 64 + ch * 8 + 4);
; __device__ __forceinline__ void prompt_unit_fox(const Args& a, int l, int b, int h, int qb, LAS unsigned char* lds) {
;     ...
;     if (pending) fox_pair_pv(st, pp, vp0 + pslot * 16384);
;     EpiPre pre; epi_preload<0>(pre, a, l, h, rowb + q0 + wid * 32, col, lane);
;     ATT_WAIT_BAR();
;     prompt_epilogue<0>(a, l, h, rowb + q0 + wid * 32, col, st, pre, wsf, (LAS float*)lds + wid * 2048, lane, r32, hi);
.LBB0_350:
	v_readlane_b32 s8, v242, 12
	v_readlane_b32 s9, v242, 13
	s_add_u32 s0, s8, s0
	s_addc_u32 s1, s9, 0
	v_lshlrev_b32_e32 v2, 2, v174
	global_load_dwordx4 v[10:13], v2, s[0:1] offset:16
	global_load_dwordx4 v[14:17], v2, s[0:1]
	v_readlane_b32 s0, v242, 28
	v_readlane_b32 s1, v242, 29
	s_mov_b32 s75, s87
	v_lshlrev_b32_e32 v4, 1, v174
	v_lshl_add_u64 v[2:3], s[0:1], 0, v[170:171]
	v_readlane_b32 s0, v242, 30
	v_readlane_b32 s1, v242, 31
	v_lshl_add_u64 v[2:3], v[2:3], 0, s[74:75]
	v_lshl_add_u64 v[2:3], v[2:3], 0, v[4:5]
	v_lshl_add_u64 v[6:7], s[0:1], 0, v[170:171]
	v_readlane_b32 s0, v242, 32
	v_lshl_add_u64 v[6:7], v[6:7], 0, s[74:75]
	v_readlane_b32 s1, v242, 33
	v_lshl_add_u64 v[6:7], v[6:7], 0, v[4:5]
	global_load_dwordx4 v[28:31], v[2:3], off
	global_load_dwordx4 v[24:27], v[6:7], off
	v_lshl_add_u64 v[2:3], s[0:1], 0, v[170:171]
	v_readlane_b32 s0, v242, 34
	v_readlane_b32 s1, v242, 35
	v_lshl_add_u64 v[2:3], v[2:3], 0, s[74:75]
	v_lshl_add_u64 v[2:3], v[2:3], 0, v[4:5]
	v_lshl_add_u64 v[6:7], s[0:1], 0, v[170:171]
	v_lshl_add_u64 v[6:7], v[6:7], 0, s[74:75]
	v_lshl_add_u64 v[6:7], v[6:7], 0, v[4:5]
	global_load_dwordx4 v[20:23], v[2:3], off
	s_nop 0
	global_load_dwordx4 v[6:9], v[6:7], off
	s_waitcnt vmcnt(6) lgkmcnt(0)
	s_barrier
	v_readlane_b32 s94, v237, 5
	v_readlane_b32 s12, v242, 36
	v_mov_b32_e32 v2, v194
	v_readlane_b32 s95, v237, 6
	v_readlane_b32 s13, v242, 37
	v_readlane_b32 s3, v237, 9
	v_readlane_b32 s14, v237, 11
	v_permlane32_swap_b32_e32 v194, v2
	v_readlane_b32 s10, v242, 14
	v_readlane_b32 s11, v242, 15
	s_and_saveexec_b64 s[0:1], s[6:7]
	s_cbranch_execz .LBB0_352
	v_add_f32_e32 v2, v194, v2
	v_div_scale_f32 v3, s[4:5], v2, v2, 1.0
	v_rcp_f32_e32 v4, v3
	v_div_scale_f32 v32, vcc, 1.0, v2, 1.0
	v_fma_f32 v33, -v3, v4, 1.0
	v_fmac_f32_e32 v4, v33, v4
	v_mul_f32_e32 v33, v32, v4
	v_fma_f32 v34, -v3, v33, v32
	v_fmac_f32_e32 v33, v34, v4
	v_fma_f32 v3, -v3, v33, v32
	v_div_fmas_f32 v3, v3, v4, v33
	v_div_fixup_f32 v2, v3, v2, 1.0
	ds_write_b32 v182, v2
.LBB0_352:
	s_or_b64 exec, exec, s[0:1]
	s_waitcnt lgkmcnt(0)
	v_add_u32_e32 v2, s78, v172
	ds_read_b128 v[32:35], v2
	ds_read_b128 v[36:39], v2 offset:32
	s_lshl_b32 s0, s77, 13
	s_add_i32 s0, s0, 0
	s_waitcnt lgkmcnt(1)
	v_mul_f32_e32 v3, v68, v32
	v_mul_f32_e32 v4, v52, v32
	v_mul_f32_e32 v40, v69, v33
	v_mul_f32_e32 v41, v53, v33
	v_mul_f32_e32 v42, v70, v34
	v_mul_f32_e32 v43, v54, v34
	v_mul_f32_e32 v44, v71, v35
	v_mul_f32_e32 v45, v55, v35
	ds_read_b128 v[32:35], v2 offset:64
	s_waitcnt lgkmcnt(1)
	v_mul_f32_e32 v46, v72, v36
	v_mul_f32_e32 v47, v56, v36
	v_mul_f32_e32 v48, v73, v37
	v_mul_f32_e32 v49, v57, v37
	v_mul_f32_e32 v50, v74, v38
	v_mul_f32_e32 v51, v58, v38
	v_mul_f32_e32 v52, v75, v39
	v_mul_f32_e32 v53, v59, v39
	ds_read_b128 v[36:39], v2 offset:96
	s_waitcnt lgkmcnt(1)
	v_mul_f32_e32 v54, v77, v33
	v_mul_f32_e32 v33, v61, v33
	v_lshlrev_b32_e32 v61, 2, v175
	v_add3_u32 v61, s0, v173, v61
	ds_write2_b32 v61, v3, v4 offset1:32
	ds_write2_b32 v61, v40, v41 offset0:64 offset1:96
	ds_write2_b32 v61, v42, v43 offset0:128 offset1:160
	ds_write2_b32 v61, v44, v45 offset0:192 offset1:224
	v_add_u32_e32 v3, 0x800, v61
	v_mul_f32_e32 v2, v76, v32
	v_mul_f32_e32 v32, v60, v32
	ds_write2_b32 v3, v46, v47 offset1:32
	ds_write2_b32 v3, v48, v49 offset0:64 offset1:96
	ds_write2_b32 v3, v50, v51 offset0:128 offset1:160
	ds_write2_b32 v3, v52, v53 offset0:192 offset1:224
	v_add_u32_e32 v3, 0x1000, v61
	v_mul_f32_e32 v55, v78, v34
	v_mul_f32_e32 v34, v62, v34
	v_mul_f32_e32 v56, v79, v35
	v_mul_f32_e32 v35, v63, v35
	s_waitcnt lgkmcnt(8)
	v_mul_f32_e32 v57, v80, v36
	v_mul_f32_e32 v36, v64, v36
	ds_write2_b32 v3, v2, v32 offset1:32
	ds_write2_b32 v3, v54, v33 offset0:64 offset1:96
	ds_write2_b32 v3, v55, v34 offset0:128 offset1:160
	ds_write2_b32 v3, v56, v35 offset0:192 offset1:224
	v_add_u32_e32 v2, 0x1800, v61
	v_mul_f32_e32 v58, v81, v37
	v_mul_f32_e32 v37, v65, v37
	v_mul_f32_e32 v59, v82, v38
	v_mul_f32_e32 v38, v66, v38
	v_mul_f32_e32 v60, v83, v39
	v_mul_f32_e32 v39, v67, v39
	ds_write2_b32 v2, v57, v36 offset1:32
	ds_write2_b32 v2, v58, v37 offset0:64 offset1:96
	ds_write2_b32 v2, v59, v38 offset0:128 offset1:160
	ds_write2_b32 v2, v60, v39 offset0:192 offset1:224
	v_and_b32_e32 v2, 7, v19
	v_lshl_add_u32 v19, v2, 5, s0
	s_waitcnt lgkmcnt(0)
	v_lshl_add_u32 v3, v1, 8, v19
	ds_read_b128 v[32:35], v3
	ds_read_b128 v[36:39], v3 offset:16
	s_waitcnt vmcnt(3)
	s_waitcnt vmcnt(0)
	v_lshlrev_b32_e32 v3, 16, v28
	v_and_b32_e32 v28, 0xffff0000, v28
	v_mul_f32_e32 v4, 0xbfb8aa3b, v3
	v_exp_f32_e32 v42, v4
	v_mul_f32_e32 v4, 0xbfb8aa3b, v28
	v_exp_f32_e32 v43, v4
	v_lshl_add_u64 v[40:41], s[12:13], 0, v[170:171]
	v_lshl_add_u64 v[40:41], v[40:41], 0, s[74:75]
	v_lshlrev_b32_e32 v4, 4, v2
	v_pk_add_f32 v[42:43], v[42:43], 1.0 op_sel_hi:[1,0]
	v_lshl_add_u64 v[40:41], v[40:41], 0, v[4:5]
	v_div_scale_f32 v46, s[0:1], v43, v43, v28
	v_rcp_f32_e32 v47, v46
	s_waitcnt lgkmcnt(1)
; #define LAS __attribute__((address_space(3)))
; __device__ __forceinline__ float bflo(unsigned w) { return __uint_as_float(w << 16); }
; __device__ __forceinline__ float bfhi(unsigned w) { return __uint_as_float(w & 0xffff0000u); }
; __device__ __forceinline__ unsigned cvtpk(float lo, float hi) { f32x2 v = {lo, hi}; bf16x2_t b = __builtin_convertvector(v, bf16x2_t); return __builtin_bit_cast(unsigned, b); }
; __device__ __forceinline__ float gate8(const f32x4& x0, const f32x4& x1, const float (&gn)[8], const u32x4& zw, bf16* orow) {
;     const float zz[8] = {bflo(zw.x), bfhi(zw.x), bflo(zw.y), bfhi(zw.y), bflo(zw.z), bfhi(zw.z), bflo(zw.w), bfhi(zw.w)};
;     const float xs[8] = {x0[0], x0[1], x0[2], x0[3], x1[0], x1[1], x1[2], x1[3]};
;     float r[8], ssq = 0.f;
; #pragma unroll
;     for (int i = 0; i < 8; ++i) { ssq += xs[i] * xs[i]; r[i] = xs[i] * gn[i] * (zz[i] / (1.0f + __expf(-zz[i]))); }
;     u32x4 w; w.x = cvtpk(r[0], r[1]); w.y = cvtpk(r[2], r[3]); w.z = cvtpk(r[4], r[5]); w.w = cvtpk(r[6], r[7]);
;     *(u32x4*)orow = w;
;     return ssq;
; }
; template <int TYPE>
; __device__ __forceinline__ void prompt_epilogue(const Args& a, int l, int h, size_t rowq  , int col, FoxState& st, const EpiPre& pre, LAS float* wsf, LAS float* stg, int lane, int r32, int hi) {
;     ...
;     for (int i = 0; i < 4; ++i) {
;         const int row = i * 8 + (lane >> 3); const size_t grow = rowq + row;
;         const f32x4 x0 = *(const LAS f32x4*)(stg + row * 64 + ch * 8), x1 = *(const LAS f32x4*)(stg + row * 64 + ch * 8 + 4);
;         float ssq = gate8(x0, x1, gn, pre.z[i], (bf16*)(a.ws + WS_HN) + grow * D + col + ch * 8);
;         ssq = sum8_dpp(ssq);
;         if (ch == 0) ((float*)(a.ws + WS_SSQ))[grow * 16 + TYPE * 8 + h] = ssq;
;     }
	v_mul_f32_e32 v4, v33, v33
	v_fmac_f32_e32 v4, v32, v32
	v_pk_mul_f32 v[44:45], v[16:17], v[34:35]
	v_fma_f32 v48, -v46, v47, 1.0
	v_fmac_f32_e32 v47, v48, v47
	v_div_scale_f32 v48, vcc, v28, v43, v28
	v_mul_f32_e32 v49, v48, v47
	v_fma_f32 v50, -v46, v49, v48
	v_fmac_f32_e32 v49, v50, v47
	v_fma_f32 v46, -v46, v49, v48
	v_div_scale_f32 v48, s[0:1], v42, v42, v3
	v_rcp_f32_e32 v50, v48
	v_div_fmas_f32 v46, v46, v47, v49
	v_div_fixup_f32 v43, v46, v43, v28
	v_and_b32_e32 v49, 0xffff0000, v29
	v_fma_f32 v28, -v48, v50, 1.0
	v_fmac_f32_e32 v50, v28, v50
	v_div_scale_f32 v28, vcc, v3, v42, v3
	v_mul_f32_e32 v46, v28, v50
	v_fma_f32 v47, -v48, v46, v28
	v_fmac_f32_e32 v46, v47, v50
	v_fma_f32 v47, -v48, v46, v28
	v_lshlrev_b32_e32 v48, 16, v29
	v_mul_f32_e32 v28, 0xbfb8aa3b, v48
	v_mul_f32_e32 v29, 0xbfb8aa3b, v49
	v_exp_f32_e32 v28, v28
	v_exp_f32_e32 v29, v29
	v_div_fmas_f32 v46, v47, v50, v46
	v_div_fixup_f32 v42, v46, v42, v3
	v_fmac_f32_e32 v4, v34, v34
	v_pk_add_f32 v[28:29], v[28:29], 1.0 op_sel_hi:[1,0]
	v_pk_mul_f32 v[32:33], v[14:15], v[32:33]
	v_div_scale_f32 v3, s[0:1], v29, v29, v49
	v_rcp_f32_e32 v46, v3
	v_fmac_f32_e32 v4, v35, v35
	v_pk_mul_f32 v[32:33], v[42:43], v[32:33]
	s_waitcnt lgkmcnt(0)
	v_fmac_f32_e32 v4, v36, v36
	v_fma_f32 v34, -v3, v46, 1.0
	v_fmac_f32_e32 v46, v34, v46
	v_div_scale_f32 v34, vcc, v49, v29, v49
	v_mul_f32_e32 v35, v34, v46
	v_fma_f32 v42, -v3, v35, v34
	v_fmac_f32_e32 v35, v42, v46
	v_fma_f32 v3, -v3, v35, v34
	v_div_scale_f32 v34, s[0:1], v28, v28, v48
	v_rcp_f32_e32 v42, v34
	v_div_fmas_f32 v3, v3, v46, v35
	v_div_fixup_f32 v29, v3, v29, v49
	v_lshlrev_b32_e32 v46, 16, v30
	v_fma_f32 v3, -v34, v42, 1.0
	v_fmac_f32_e32 v42, v3, v42
	v_div_scale_f32 v3, vcc, v48, v28, v48
	v_mul_f32_e32 v35, v3, v42
	v_fma_f32 v43, -v34, v35, v3
	v_fmac_f32_e32 v35, v43, v42
	v_fma_f32 v3, -v34, v35, v3
	v_and_b32_e32 v30, 0xffff0000, v30
	v_div_fmas_f32 v3, v3, v42, v35
	v_mul_f32_e32 v34, 0xbfb8aa3b, v46
	v_mul_f32_e32 v35, 0xbfb8aa3b, v30
	v_exp_f32_e32 v34, v34
	v_exp_f32_e32 v35, v35
	v_div_fixup_f32 v28, v3, v28, v48
	v_pk_mul_f32 v[42:43], v[28:29], v[44:45]
	v_fmac_f32_e32 v4, v37, v37
	v_pk_add_f32 v[28:29], v[34:35], 1.0 op_sel_hi:[1,0]
	v_pk_mul_f32 v[36:37], v[10:11], v[36:37]
	v_div_scale_f32 v3, s[0:1], v29, v29, v30
	v_rcp_f32_e32 v44, v3
	v_pk_mul_f32 v[34:35], v[12:13], v[38:39]
	v_fmac_f32_e32 v4, v38, v38
	v_fmac_f32_e32 v4, v39, v39
	v_fma_f32 v45, -v3, v44, 1.0
	v_fmac_f32_e32 v44, v45, v44
	v_div_scale_f32 v45, vcc, v30, v29, v30
	v_mul_f32_e32 v47, v45, v44
	v_fma_f32 v48, -v3, v47, v45
	v_fmac_f32_e32 v47, v48, v44
	v_fma_f32 v3, -v3, v47, v45
	v_div_scale_f32 v45, s[0:1], v28, v28, v46
	v_rcp_f32_e32 v48, v45
	v_div_fmas_f32 v3, v3, v44, v47
	v_div_fixup_f32 v29, v3, v29, v30
	v_and_b32_e32 v47, 0xffff0000, v31
	v_fma_f32 v3, -v45, v48, 1.0
	v_fmac_f32_e32 v48, v3, v48
	v_div_scale_f32 v3, vcc, v46, v28, v46
	v_mul_f32_e32 v44, v3, v48
	v_fma_f32 v30, -v45, v44, v3
	v_fmac_f32_e32 v44, v30, v48
	v_fma_f32 v3, -v45, v44, v3
	v_lshlrev_b32_e32 v45, 16, v31
	v_mul_f32_e32 v30, 0xbfb8aa3b, v45
	v_mul_f32_e32 v31, 0xbfb8aa3b, v47
	v_exp_f32_e32 v30, v30
	v_exp_f32_e32 v31, v31
	v_div_fmas_f32 v3, v3, v48, v44
	v_div_fixup_f32 v28, v3, v28, v46
	v_pk_mul_f32 v[36:37], v[28:29], v[36:37]
	v_pk_add_f32 v[30:31], v[30:31], 1.0 op_sel_hi:[1,0]
	v_cmp_eq_u32_e64 s[6:7], 0, v2
	v_div_scale_f32 v3, s[0:1], v31, v31, v47
	v_rcp_f32_e32 v44, v3
	s_nop 0
	v_fma_f32 v28, -v3, v44, 1.0
	v_fmac_f32_e32 v44, v28, v44
	v_div_scale_f32 v28, vcc, v47, v31, v47
	v_mul_f32_e32 v29, v28, v44
	v_fma_f32 v38, -v3, v29, v28
	v_fmac_f32_e32 v29, v38, v44
	v_fma_f32 v3, -v3, v29, v28
	v_div_scale_f32 v28, s[0:1], v30, v30, v45
	v_rcp_f32_e32 v38, v28
	v_div_fmas_f32 v3, v3, v44, v29
	v_div_fixup_f32 v29, v3, v31, v47
	v_fma_f32 v3, -v28, v38, 1.0
	v_fmac_f32_e32 v38, v3, v38
	v_div_scale_f32 v3, vcc, v45, v30, v45
	v_mul_f32_e32 v31, v3, v38
	v_fma_f32 v39, -v28, v31, v3
	v_fmac_f32_e32 v31, v39, v38
	v_fma_f32 v3, -v28, v31, v3
	v_div_fmas_f32 v3, v3, v38, v31
	v_div_fixup_f32 v28, v3, v30, v45
	v_pk_mul_f32 v[34:35], v[28:29], v[34:35]
	v_add_f32_dpp v3, v4, v4 quad_perm:[1,0,3,2] row_mask:0xf bank_mask:0xf bound_ctrl:1
	v_mov_b32_e32 v4, v5
	v_cvt_pk_bf16_f32 v28, v32, v33
	v_add_f32_dpp v3, v3, v3 quad_perm:[2,3,0,1] row_mask:0xf bank_mask:0xf bound_ctrl:1
	v_cvt_pk_bf16_f32 v29, v42, v43
	v_cvt_pk_bf16_f32 v30, v36, v37
	v_cvt_pk_bf16_f32 v31, v34, v35
	v_mov_b32_dpp v4, v3 row_half_mirror row_mask:0xf bank_mask:0xf
	global_store_dwordx4 v[40:41], v[28:31], off
	s_and_saveexec_b64 s[0:1], s[6:7]
	s_cbranch_execz .LBB0_354
	v_readlane_b32 s4, v242, 47
	v_lshlrev_b64 v[28:29], 6, v[168:169]
	v_readlane_b32 s5, v242, 48
	v_add_f32_e32 v3, v3, v4
	s_nop 0
	v_lshl_add_u64 v[28:29], s[4:5], 0, v[28:29]
	s_lshl_b32 s4, s3, 2
	s_mov_b32 s5, s87
	v_lshl_add_u64 v[28:29], v[28:29], 0, s[4:5]
	global_store_dword v[28:29], v3, off

; __device__ __forceinline__ float bflo(unsigned w) { return __uint_as_float(w << 16); }
; __device__ __forceinline__ float bfhi(unsigned w) { return __uint_as_float(w & 0xffff0000u); }
; __device__ __forceinline__ unsigned cvt_pk_bf16(float lo, float hi) { unsigned r; asm volatile("v_cvt_pk_bf16_f32 %0, %1, %2" : "=v"(r) : "v"(lo), "v"(hi)); return r; }
;     __device__ __forceinline__ void operator()(const pg8::f32x4 (&acc)[2][2][4][2], const pg8::Unit& u, int ui, int wr, int wc, int fr, int fq) const {
;     ...
;             for (int m = 0; m < 4; ++m) { const size_t ro = off0 + (size_t)(ai * 128 + m * 16) * D;
; #pragma unroll
;                 for (int bj = 0; bj < 2; ++bj) {
;                     if (l == 0) { x[m][bj][0] = *(const pg8::f32x4*)(xin_p + ro + bj * 128); x[m][bj][1] = *(const pg8::f32x4*)(xin_p + ro + bj * 128 + 4); }
;                     else { const u32x4 w = *(const u32x4*)(xb + ro + bj * 128);
;                            x[m][bj][0] = (pg8::f32x4){bflo(w.x), bfhi(w.x), bflo(w.y), bfhi(w.y)}; x[m][bj][1] = (pg8::f32x4){bflo(w.z), bfhi(w.z), bflo(w.w), bfhi(w.w)}; } } }
; #pragma unroll
;             for (int m = 0; m < 4; ++m) { const size_t ro = off0 + (size_t)(ai * 128 + m * 16) * D; const float rB = tb[(ai * 128 + m * 16) * 2];
; #pragma unroll
;                 for (int bj = 0; bj < 2; ++bj) {
;                     const pg8::f32x4 y0 = x[m][bj][0] + acc[ai][bj][m][0] * rB, y1 = x[m][bj][1] + acc[ai][bj][m][1] * rB;
;                     u32x4 o; o.x = pg8::cvt_pk_bf16(y0[0], y0[1]); o.y = pg8::cvt_pk_bf16(y0[2], y0[3]); o.z = pg8::cvt_pk_bf16(y1[0], y1[1]); o.w = pg8::cvt_pk_bf16(y1[2], y1[3]);
;                     *(u32x4*)(xb + ro + bj * 128) = o; } }
.LBB0_648:
	s_and_saveexec_b64 s[94:95], s[4:5]
	v_lshl_or_b32 v234, s44, 8, v0
	v_ashrrev_i32_e32 v235, 31, v234
	v_lshlrev_b64 v[234:235], 6, v[234:235]
	v_lshl_add_u64 v[234:235], s[10:11], 0, v[234:235]
	global_load_dwordx4 v[238:241], v[234:235], off
	global_load_dwordx4 v[244:247], v[234:235], off offset:16
	global_load_dwordx4 v[248:251], v[234:235], off offset:32
	global_load_dwordx4 v[252:255], v[234:235], off offset:48
	s_mov_b64 exec, s[94:95]
	s_nop 1
	s_ashr_i32 s49, s48, 31
	s_lshl_b32 s43, s83, 8
	s_lshl_b64 s[2:3], s[48:49], 18
	s_ashr_i32 s45, s43, 31
	s_add_u32 s2, s2, s43
	s_addc_u32 s3, s3, s45
	v_lshl_add_u64 v[4:5], s[2:3], 0, v[144:145]
	v_lshl_add_u64 v[154:155], v[4:5], 2, s[12:13]
	global_load_dwordx4 v[162:165], v[154:155], off
	global_load_dwordx4 v[166:169], v[154:155], off offset:16
	global_load_dwordx4 v[170:173], v[154:155], off offset:512
	global_load_dwordx4 v[174:177], v[154:155], off offset:528
	s_mov_b64 s[2:3], 0x10000
	v_add_co_u32_e32 v156, vcc, s66, v154
	v_lshl_add_u64 v[182:183], v[154:155], 0, s[2:3]
	s_nop 0
	v_addc_co_u32_e32 v157, vcc, 0, v155, vcc
	s_mov_b64 s[2:3], 0x10200
	global_load_dwordx4 v[178:181], v[156:157], off
	s_nop 0
	global_load_dwordx4 v[182:185], v[182:183], off offset:16
	s_mov_b32 s43, 0x20000
	global_load_dwordx4 v[186:189], v[156:157], off offset:512
	v_lshl_add_u64 v[156:157], v[154:155], 0, s[2:3]
	global_load_dwordx4 v[190:193], v[156:157], off offset:16
	v_add_co_u32_e32 v156, vcc, s43, v154
	s_mov_b64 s[2:3], 0x20000
	s_nop 0
	v_addc_co_u32_e32 v157, vcc, 0, v155, vcc
	global_load_dwordx4 v[194:197], v[156:157], off
	global_load_dwordx4 v[202:205], v[156:157], off offset:512
	v_lshl_add_u64 v[198:199], v[154:155], 0, s[2:3]
	global_load_dwordx4 v[198:201], v[198:199], off offset:16
	s_mov_b64 s[2:3], 0x20200
	v_lshl_add_u64 v[156:157], v[154:155], 0, s[2:3]
	global_load_dwordx4 v[206:209], v[156:157], off offset:16
	s_mov_b64 s[2:3], 0x30000
	v_lshl_add_u64 v[214:215], v[154:155], 0, s[2:3]
	global_load_dwordx4 v[214:217], v[214:215], off offset:16
	v_add_co_u32_e32 v156, vcc, s73, v154
	s_add_i32 s45, 0, 0x20400
	s_nop 0
	v_addc_co_u32_e32 v157, vcc, 0, v155, vcc
	global_load_dwordx4 v[210:213], v[156:157], off
	v_add_u32_e32 v3, s45, v160
	v_lshl_add_u64 v[222:223], v[154:155], 0, s[22:23]
	ds_read_b32 v160, v3 offset:4
	global_load_dwordx4 v[218:221], v[156:157], off offset:512
	s_nop 0
	global_load_dwordx4 v[222:225], v[222:223], off offset:16
	v_lshl_add_u64 v[4:5], v[4:5], 1, s[16:17]
	s_mov_b32 s43, 0x8000
	s_mov_b32 s2, 0x18000
	v_readlane_b32 s84, v242, 6
	v_readlane_b32 s85, v242, 7
	s_waitcnt lgkmcnt(0)
	s_waitcnt vmcnt(15)
	v_pk_fma_f32 v[132:133], v[132:133], v[160:161], v[164:165] op_sel_hi:[1,0,1]
	v_pk_fma_f32 v[130:131], v[130:131], v[160:161], v[162:163] op_sel_hi:[1,0,1]
	s_waitcnt vmcnt(14)
	v_pk_fma_f32 v[128:129], v[128:129], v[160:161], v[168:169] op_sel_hi:[1,0,1]
	v_pk_fma_f32 v[126:127], v[126:127], v[160:161], v[166:167] op_sel_hi:[1,0,1]
	s_waitcnt vmcnt(13)
	v_pk_fma_f32 v[124:125], v[124:125], v[160:161], v[172:173] op_sel_hi:[1,0,1]
	v_pk_fma_f32 v[122:123], v[122:123], v[160:161], v[170:171] op_sel_hi:[1,0,1]
	s_waitcnt vmcnt(12)
	v_pk_fma_f32 v[156:157], v[120:121], v[160:161], v[176:177] op_sel_hi:[1,0,1]
	v_pk_fma_f32 v[160:161], v[118:119], v[160:161], v[174:175] op_sel_hi:[1,0,1]
	v_cvt_pk_bf16_f32 v118, v130, v131
	v_cvt_pk_bf16_f32 v119, v132, v133
	v_cvt_pk_bf16_f32 v120, v126, v127
	v_cvt_pk_bf16_f32 v121, v128, v129
	global_store_dwordx4 v[4:5], v[118:121], off
	v_lshl_add_u64 v[130:131], v[154:155], 0, s[40:41]
	s_nop 0
	v_cvt_pk_bf16_f32 v118, v122, v123
	v_cvt_pk_bf16_f32 v119, v124, v125
	v_cvt_pk_bf16_f32 v120, v160, v161
	v_cvt_pk_bf16_f32 v121, v156, v157
	ds_read_b32 v122, v3 offset:132
	v_add_co_u32_e32 v124, vcc, s43, v4
	global_store_dwordx4 v[4:5], v[118:121], off offset:256
	s_nop 0
	v_addc_co_u32_e32 v125, vcc, 0, v5, vcc
	s_waitcnt lgkmcnt(0)
	s_waitcnt vmcnt(13)
	v_pk_fma_f32 v[116:117], v[116:117], v[122:123], v[180:181] op_sel_hi:[1,0,1]
	v_pk_fma_f32 v[114:115], v[114:115], v[122:123], v[178:179] op_sel_hi:[1,0,1]
	s_waitcnt vmcnt(12)
	v_pk_fma_f32 v[112:113], v[112:113], v[122:123], v[184:185] op_sel_hi:[1,0,1]
	v_pk_fma_f32 v[110:111], v[110:111], v[122:123], v[182:183] op_sel_hi:[1,0,1]
	s_waitcnt vmcnt(11)
	v_pk_fma_f32 v[106:107], v[106:107], v[122:123], v[186:187] op_sel_hi:[1,0,1]
	s_waitcnt vmcnt(10)
	v_pk_fma_f32 v[118:119], v[104:105], v[122:123], v[192:193] op_sel_hi:[1,0,1]
	v_pk_fma_f32 v[120:121], v[102:103], v[122:123], v[190:191] op_sel_hi:[1,0,1]
	v_cvt_pk_bf16_f32 v102, v114, v115
	v_cvt_pk_bf16_f32 v103, v116, v117
	v_cvt_pk_bf16_f32 v104, v110, v111
	v_cvt_pk_bf16_f32 v105, v112, v113
	v_pk_fma_f32 v[108:109], v[108:109], v[122:123], v[188:189] op_sel_hi:[1,0,1]
	global_store_dwordx4 v[124:125], v[102:105], off
	v_lshl_add_u64 v[114:115], v[154:155], 0, s[36:37]
	v_lshl_add_u64 v[122:123], v[154:155], 0, s[38:39]
	v_cvt_pk_bf16_f32 v102, v106, v107
	v_cvt_pk_bf16_f32 v103, v108, v109
	v_cvt_pk_bf16_f32 v104, v120, v121
	v_cvt_pk_bf16_f32 v105, v118, v119
	ds_read_b32 v106, v3 offset:260
	global_store_dwordx4 v[124:125], v[102:105], off offset:256
	s_waitcnt lgkmcnt(0)
	s_waitcnt vmcnt(11)
	v_pk_fma_f32 v[98:99], v[98:99], v[106:107], v[194:195] op_sel_hi:[1,0,1]
	s_waitcnt vmcnt(9)
; __device__ __forceinline__ float bflo(unsigned w) { return __uint_as_float(w << 16); }
; __device__ __forceinline__ float bfhi(unsigned w) { return __uint_as_float(w & 0xffff0000u); }
; __device__ __forceinline__ unsigned cvt_pk_bf16(float lo, float hi) { unsigned r; asm volatile("v_cvt_pk_bf16_f32 %0, %1, %2" : "=v"(r) : "v"(lo), "v"(hi)); return r; }
;     __device__ __forceinline__ void operator()(const pg8::f32x4 (&acc)[2][2][4][2], const pg8::Unit& u, int ui, int wr, int wc, int fr, int fq) const {
;     ...
;             for (int m = 0; m < 4; ++m) { const size_t ro = off0 + (size_t)(ai * 128 + m * 16) * D;
; #pragma unroll
;                 for (int bj = 0; bj < 2; ++bj) {
;                     if (l == 0) { x[m][bj][0] = *(const pg8::f32x4*)(xin_p + ro + bj * 128); x[m][bj][1] = *(const pg8::f32x4*)(xin_p + ro + bj * 128 + 4); }
;                     else { const u32x4 w = *(const u32x4*)(xb + ro + bj * 128);
;                            x[m][bj][0] = (pg8::f32x4){bflo(w.x), bfhi(w.x), bflo(w.y), bfhi(w.y)}; x[m][bj][1] = (pg8::f32x4){bflo(w.z), bfhi(w.z), bflo(w.w), bfhi(w.w)}; } } }
; #pragma unroll
;             for (int m = 0; m < 4; ++m) { const size_t ro = off0 + (size_t)(ai * 128 + m * 16) * D; const float rB = tb[(ai * 128 + m * 16) * 2];
; #pragma unroll
;                 for (int bj = 0; bj < 2; ++bj) {
;                     const pg8::f32x4 y0 = x[m][bj][0] + acc[ai][bj][m][0] * rB, y1 = x[m][bj][1] + acc[ai][bj][m][1] * rB;
;                     u32x4 o; o.x = pg8::cvt_pk_bf16(y0[0], y0[1]); o.y = pg8::cvt_pk_bf16(y0[2], y0[3]); o.z = pg8::cvt_pk_bf16(y1[0], y1[1]); o.w = pg8::cvt_pk_bf16(y1[2], y1[3]);
;                     *(u32x4*)(xb + ro + bj * 128) = o; } }
	v_pk_fma_f32 v[102:103], v[96:97], v[106:107], v[200:201] op_sel_hi:[1,0,1]
	v_pk_fma_f32 v[96:97], v[94:95], v[106:107], v[198:199] op_sel_hi:[1,0,1]
	v_cvt_pk_bf16_f32 v94, v98, v99
	v_add_co_u32_e32 v98, vcc, s66, v4
	v_pk_fma_f32 v[100:101], v[100:101], v[106:107], v[196:197] op_sel_hi:[1,0,1]
	s_nop 0
	v_addc_co_u32_e32 v99, vcc, 0, v5, vcc
	v_cvt_pk_bf16_f32 v95, v100, v101
	v_cvt_pk_bf16_f32 v96, v96, v97
	v_cvt_pk_bf16_f32 v97, v102, v103
	global_store_dwordx4 v[98:99], v[94:97], off
	v_pk_fma_f32 v[90:91], v[90:91], v[106:107], v[202:203] op_sel_hi:[1,0,1]
	v_pk_fma_f32 v[92:93], v[92:93], v[106:107], v[204:205] op_sel_hi:[1,0,1]
	s_waitcnt vmcnt(9)
	v_pk_fma_f32 v[94:95], v[88:89], v[106:107], v[208:209] op_sel_hi:[1,0,1]
	v_pk_fma_f32 v[88:89], v[86:87], v[106:107], v[206:207] op_sel_hi:[1,0,1]
	v_cvt_pk_bf16_f32 v86, v90, v91
	v_cvt_pk_bf16_f32 v87, v92, v93
	v_lshl_add_u64 v[106:107], v[154:155], 0, s[34:35]
	v_cvt_pk_bf16_f32 v88, v88, v89
	v_cvt_pk_bf16_f32 v89, v94, v95
	ds_read_b32 v90, v3 offset:388
	global_store_dwordx4 v[98:99], v[86:89], off offset:256
	v_lshl_add_u64 v[98:99], v[154:155], 0, s[30:31]
	s_waitcnt lgkmcnt(0)
	s_waitcnt vmcnt(8)
	v_pk_fma_f32 v[82:83], v[82:83], v[90:91], v[210:211] op_sel_hi:[1,0,1]
	v_pk_fma_f32 v[86:87], v[80:81], v[90:91], v[216:217] op_sel_hi:[1,0,1]
	v_pk_fma_f32 v[80:81], v[78:79], v[90:91], v[214:215] op_sel_hi:[1,0,1]
	v_cvt_pk_bf16_f32 v78, v82, v83
	v_add_co_u32_e32 v82, vcc, s2, v4
	v_pk_fma_f32 v[84:85], v[84:85], v[90:91], v[212:213] op_sel_hi:[1,0,1]
	s_nop 0
	v_addc_co_u32_e32 v83, vcc, 0, v5, vcc
	v_cvt_pk_bf16_f32 v79, v84, v85
	v_cvt_pk_bf16_f32 v80, v80, v81
	v_cvt_pk_bf16_f32 v81, v86, v87
	global_store_dwordx4 v[82:83], v[78:81], off
	s_waitcnt vmcnt(8)
	v_pk_fma_f32 v[76:77], v[76:77], v[90:91], v[220:221] op_sel_hi:[1,0,1]
	v_pk_fma_f32 v[74:75], v[74:75], v[90:91], v[218:219] op_sel_hi:[1,0,1]
	s_waitcnt vmcnt(7)
	v_pk_fma_f32 v[78:79], v[72:73], v[90:91], v[224:225] op_sel_hi:[1,0,1]
	v_pk_fma_f32 v[72:73], v[70:71], v[90:91], v[222:223] op_sel_hi:[1,0,1]
	v_cvt_pk_bf16_f32 v70, v74, v75
	v_cvt_pk_bf16_f32 v71, v76, v77
	v_lshl_add_u64 v[74:75], v[154:155], 0, s[24:25]
	v_cvt_pk_bf16_f32 v72, v72, v73
	v_cvt_pk_bf16_f32 v73, v78, v79
	global_store_dwordx4 v[82:83], v[70:73], off offset:256
	v_add_co_u32_e32 v78, vcc, s74, v154
	v_lshl_add_u64 v[82:83], v[154:155], 0, s[26:27]
	s_nop 0
	v_addc_co_u32_e32 v79, vcc, 0, v155, vcc
	global_load_dwordx4 v[70:73], v[78:79], off
	s_nop 0
	global_load_dwordx4 v[74:77], v[74:75], off offset:16
	s_nop 0
	global_load_dwordx4 v[78:81], v[78:79], off offset:512
	v_add_co_u32_e32 v94, vcc, s75, v154
	global_load_dwordx4 v[82:85], v[82:83], off offset:16
	s_nop 0
	v_addc_co_u32_e32 v95, vcc, 0, v155, vcc
	global_load_dwordx4 v[86:89], v[94:95], off
	v_lshl_add_u64 v[90:91], v[154:155], 0, s[28:29]
	global_load_dwordx4 v[90:93], v[90:91], off offset:16
	s_nop 0
	global_load_dwordx4 v[94:97], v[94:95], off offset:512
	v_add_co_u32_e32 v110, vcc, s76, v154
	global_load_dwordx4 v[98:101], v[98:99], off offset:16
	s_nop 0
	v_addc_co_u32_e32 v111, vcc, 0, v155, vcc
	global_load_dwordx4 v[102:105], v[110:111], off
	s_nop 0
	global_load_dwordx4 v[106:109], v[106:107], off offset:16
	s_nop 0
	global_load_dwordx4 v[110:113], v[110:111], off offset:512
	v_add_co_u32_e32 v126, vcc, s77, v154
	global_load_dwordx4 v[114:117], v[114:115], off offset:16
	s_nop 0
	v_addc_co_u32_e32 v127, vcc, 0, v155, vcc
	global_load_dwordx4 v[118:121], v[126:127], off
	s_nop 0
	global_load_dwordx4 v[122:125], v[122:123], off offset:16
	ds_read_b32 v154, v3 offset:1028
	global_load_dwordx4 v[126:129], v[126:127], off offset:512
	s_nop 0
	global_load_dwordx4 v[130:133], v[130:131], off offset:16
	v_add_co_u32_e32 v156, vcc, s78, v4
	s_mov_b64 s[2:3], -1
	s_nop 0
	v_addc_co_u32_e32 v157, vcc, 0, v5, vcc
	s_waitcnt vmcnt(15) lgkmcnt(0)
	v_pk_fma_f32 v[68:69], v[68:69], v[154:155], v[72:73] op_sel_hi:[1,0,1]
	v_pk_fma_f32 v[66:67], v[66:67], v[154:155], v[70:71] op_sel_hi:[1,0,1]
	s_waitcnt vmcnt(14)
	v_pk_fma_f32 v[64:65], v[64:65], v[154:155], v[76:77] op_sel_hi:[1,0,1]
	v_pk_fma_f32 v[62:63], v[62:63], v[154:155], v[74:75] op_sel_hi:[1,0,1]
	s_waitcnt vmcnt(13)
; __device__ __forceinline__ unsigned cvt_pk_bf16(float lo, float hi) { unsigned r; asm volatile("v_cvt_pk_bf16_f32 %0, %1, %2" : "=v"(r) : "v"(lo), "v"(hi)); return r; }
;     __device__ __forceinline__ void operator()(const pg8::f32x4 (&acc)[2][2][4][2], const pg8::Unit& u, int ui, int wr, int wc, int fr, int fq) const {
;     ...
; #pragma unroll
;             for (int m = 0; m < 4; ++m) { const size_t ro = off0 + (size_t)(ai * 128 + m * 16) * D; const float rB = tb[(ai * 128 + m * 16) * 2];
; #pragma unroll
;                 for (int bj = 0; bj < 2; ++bj) {
;                     const pg8::f32x4 y0 = x[m][bj][0] + acc[ai][bj][m][0] * rB, y1 = x[m][bj][1] + acc[ai][bj][m][1] * rB;
;                     u32x4 o; o.x = pg8::cvt_pk_bf16(y0[0], y0[1]); o.y = pg8::cvt_pk_bf16(y0[2], y0[3]); o.z = pg8::cvt_pk_bf16(y1[0], y1[1]); o.w = pg8::cvt_pk_bf16(y1[2], y1[3]);
;                     *(u32x4*)(xb + ro + bj * 128) = o; } }
	v_pk_fma_f32 v[58:59], v[58:59], v[154:155], v[78:79] op_sel_hi:[1,0,1]
	s_waitcnt vmcnt(12)
	v_pk_fma_f32 v[70:71], v[56:57], v[154:155], v[84:85] op_sel_hi:[1,0,1]
	v_pk_fma_f32 v[72:73], v[54:55], v[154:155], v[82:83] op_sel_hi:[1,0,1]
	v_cvt_pk_bf16_f32 v54, v66, v67
	v_cvt_pk_bf16_f32 v55, v68, v69
	v_cvt_pk_bf16_f32 v56, v62, v63
	v_cvt_pk_bf16_f32 v57, v64, v65
	v_pk_fma_f32 v[60:61], v[60:61], v[154:155], v[80:81] op_sel_hi:[1,0,1]
	global_store_dwordx4 v[156:157], v[54:57], off
	s_nop 1
	v_cvt_pk_bf16_f32 v54, v58, v59
	v_cvt_pk_bf16_f32 v55, v60, v61
	v_cvt_pk_bf16_f32 v56, v72, v73
	v_cvt_pk_bf16_f32 v57, v70, v71
	ds_read_b32 v58, v3 offset:1156
	global_store_dwordx4 v[156:157], v[54:57], off offset:256
	s_waitcnt vmcnt(13) lgkmcnt(0)
	v_pk_fma_f32 v[50:51], v[50:51], v[58:59], v[86:87] op_sel_hi:[1,0,1]
	s_waitcnt vmcnt(12)
	v_pk_fma_f32 v[54:55], v[48:49], v[58:59], v[92:93] op_sel_hi:[1,0,1]
	v_pk_fma_f32 v[48:49], v[46:47], v[58:59], v[90:91] op_sel_hi:[1,0,1]
	v_cvt_pk_bf16_f32 v46, v50, v51
	v_add_co_u32_e32 v50, vcc, s79, v4
	v_pk_fma_f32 v[52:53], v[52:53], v[58:59], v[88:89] op_sel_hi:[1,0,1]
	s_nop 0
	v_addc_co_u32_e32 v51, vcc, 0, v5, vcc
	v_cvt_pk_bf16_f32 v47, v52, v53
	v_cvt_pk_bf16_f32 v48, v48, v49
	v_cvt_pk_bf16_f32 v49, v54, v55
	global_store_dwordx4 v[50:51], v[46:49], off
	s_waitcnt vmcnt(12)
	v_pk_fma_f32 v[42:43], v[42:43], v[58:59], v[94:95] op_sel_hi:[1,0,1]
	v_pk_fma_f32 v[44:45], v[44:45], v[58:59], v[96:97] op_sel_hi:[1,0,1]
	s_waitcnt vmcnt(11)
	v_pk_fma_f32 v[46:47], v[40:41], v[58:59], v[100:101] op_sel_hi:[1,0,1]
	v_pk_fma_f32 v[40:41], v[38:39], v[58:59], v[98:99] op_sel_hi:[1,0,1]
	v_cvt_pk_bf16_f32 v38, v42, v43
	v_cvt_pk_bf16_f32 v39, v44, v45
	s_nop 0
	v_cvt_pk_bf16_f32 v40, v40, v41
	v_cvt_pk_bf16_f32 v41, v46, v47
	ds_read_b32 v42, v3 offset:1284
	global_store_dwordx4 v[50:51], v[38:41], off offset:256
	s_waitcnt vmcnt(11) lgkmcnt(0)
	v_pk_fma_f32 v[34:35], v[34:35], v[42:43], v[102:103] op_sel_hi:[1,0,1]
	s_waitcnt vmcnt(10)
	v_pk_fma_f32 v[38:39], v[32:33], v[42:43], v[108:109] op_sel_hi:[1,0,1]
	v_pk_fma_f32 v[32:33], v[30:31], v[42:43], v[106:107] op_sel_hi:[1,0,1]
	v_cvt_pk_bf16_f32 v30, v34, v35
	v_add_co_u32_e32 v34, vcc, s80, v4
	v_pk_fma_f32 v[36:37], v[36:37], v[42:43], v[104:105] op_sel_hi:[1,0,1]
	s_nop 0
	v_addc_co_u32_e32 v35, vcc, 0, v5, vcc
	v_cvt_pk_bf16_f32 v31, v36, v37
	v_cvt_pk_bf16_f32 v32, v32, v33
	v_cvt_pk_bf16_f32 v33, v38, v39
	global_store_dwordx4 v[34:35], v[30:33], off
	s_waitcnt vmcnt(10)
	v_pk_fma_f32 v[26:27], v[26:27], v[42:43], v[110:111] op_sel_hi:[1,0,1]
	v_pk_fma_f32 v[28:29], v[28:29], v[42:43], v[112:113] op_sel_hi:[1,0,1]
	s_waitcnt vmcnt(9)
	v_pk_fma_f32 v[30:31], v[24:25], v[42:43], v[116:117] op_sel_hi:[1,0,1]
	v_pk_fma_f32 v[24:25], v[22:23], v[42:43], v[114:115] op_sel_hi:[1,0,1]
	v_cvt_pk_bf16_f32 v22, v26, v27
	v_cvt_pk_bf16_f32 v23, v28, v29
	s_nop 0
	v_cvt_pk_bf16_f32 v24, v24, v25
	v_cvt_pk_bf16_f32 v25, v30, v31
	ds_read_b32 v26, v3 offset:1412
	global_store_dwordx4 v[34:35], v[22:25], off offset:256
	s_waitcnt vmcnt(9) lgkmcnt(0)
	v_pk_fma_f32 v[18:19], v[18:19], v[26:27], v[118:119] op_sel_hi:[1,0,1]
	s_waitcnt vmcnt(8)
	v_pk_fma_f32 v[22:23], v[16:17], v[26:27], v[124:125] op_sel_hi:[1,0,1]
	v_pk_fma_f32 v[16:17], v[14:15], v[26:27], v[122:123] op_sel_hi:[1,0,1]
	v_cvt_pk_bf16_f32 v14, v18, v19
	v_add_co_u32_e32 v18, vcc, s81, v4
	s_waitcnt vmcnt(6)
	v_pk_fma_f32 v[6:7], v[6:7], v[26:27], v[130:131] op_sel_hi:[1,0,1]
	v_addc_co_u32_e32 v19, vcc, 0, v5, vcc
	v_pk_fma_f32 v[4:5], v[10:11], v[26:27], v[126:127] op_sel_hi:[1,0,1]
	v_pk_fma_f32 v[20:21], v[20:21], v[26:27], v[120:121] op_sel_hi:[1,0,1]
	v_pk_fma_f32 v[12:13], v[12:13], v[26:27], v[128:129] op_sel_hi:[1,0,1]
	v_cvt_pk_bf16_f32 v15, v20, v21
	v_cvt_pk_bf16_f32 v16, v16, v17
	v_cvt_pk_bf16_f32 v17, v22, v23
	global_store_dwordx4 v[18:19], v[14:17], off
	v_pk_fma_f32 v[8:9], v[8:9], v[26:27], v[132:133] op_sel_hi:[1,0,1]
	v_cvt_pk_bf16_f32 v4, v4, v5
	v_cvt_pk_bf16_f32 v5, v12, v13
	v_cvt_pk_bf16_f32 v6, v6, v7
	s_andn2_b64 vcc, exec, s[6:7]
	v_cvt_pk_bf16_f32 v7, v8, v9
	global_store_dwordx4 v[18:19], v[4:7], off offset:256
	s_cbranch_vccnz .LBB0_633
	s_andn2_b64 vcc, exec, s[14:15]
	s_cbranch_vccnz .LBB0_632
	s_barrier
	s_branch .LBB0_632

; #define ATT_WAIT_BAR() asm volatile("s_waitcnt vmcnt(0) lgkmcnt(0)\n\ts_barrier" ::: "memory")
; template <int TYPE>
; __device__ __forceinline__ void epi_preload(EpiPre& e, const Args& a, int l, int h, size_t rowq, int col, int lane) {
;     const int ch = lane & 7;
;     const float* gp = (TYPE == 0 ? a.gn_a : a.gn_b) + (size_t)l * W + h * HD + ch * 8;
;     e.g0 = *(const f32x4*)gp; e.g1 = *(const f32x4*)(gp + 4);
; #pragma unroll
;     for (int i = 0; i < 4; ++i) e.z[i] = *(const u32x4*)((const bf16*)(a.ws + WS_Z) + (rowq + i * 8 + (lane >> 3)) * D + col + ch * 8);
; }
; __device__ __forceinline__ void prompt_unit_sb(const Args& a, int l, int b, int h, int qb, LAS unsigned char* lds) {
;     ...
;     EpiPre pre; epi_preload<1>(pre, a, l, h, rowb + q0 + wid * 32, col, lane);
;     ATT_WAIT_BAR();
.LBB0_1000:
	v_readlane_b32 s8, v242, 12
	v_readlane_b32 s10, v242, 14
	v_readlane_b32 s11, v242, 15
	s_add_u32 s2, s10, s92
	v_readlane_b32 s94, v242, 38
	s_addc_u32 s3, s11, 0
	v_lshlrev_b32_e32 v2, 2, v168
	v_readlane_b32 s95, v242, 39
	global_load_dwordx4 v[6:9], v2, s[2:3] offset:2064
	global_load_dwordx4 v[14:17], v2, s[2:3] offset:2048
	v_lshl_add_u64 v[2:3], s[94:95], 0, v[162:163]
	s_mov_b32 s79, s87
	v_lshl_add_u64 v[2:3], v[2:3], 0, s[78:79]
	v_lshlrev_b32_e32 v4, 1, v168
	v_lshl_add_u64 v[2:3], v[2:3], 0, v[4:5]
	global_load_dwordx4 v[60:63], v[2:3], off offset:1024
	v_readlane_b32 s2, v242, 47
	v_readlane_b32 s3, v242, 48
	s_lshl_b32 s1, s84, 13
	s_add_i32 s1, s1, 0
	v_lshl_add_u64 v[2:3], s[2:3], 0, v[162:163]
	v_lshl_add_u64 v[2:3], v[2:3], 0, s[78:79]
	v_readlane_b32 s2, v237, 9
	v_lshl_add_u64 v[2:3], v[2:3], 0, v[4:5]
	v_readlane_b32 s3, v237, 10
	global_load_dwordx4 v[56:59], v[2:3], off offset:1024
	v_readlane_b32 s96, v242, 30
	v_lshl_add_u64 v[2:3], s[2:3], 0, v[162:163]
	v_lshl_add_u64 v[2:3], v[2:3], 0, s[78:79]
	v_readlane_b32 s2, v237, 5
	v_lshl_add_u64 v[2:3], v[2:3], 0, v[4:5]
	v_readlane_b32 s3, v237, 6
	global_load_dwordx4 v[52:55], v[2:3], off offset:1024
	v_readlane_b32 s97, v242, 31
	v_lshl_add_u64 v[2:3], s[2:3], 0, v[162:163]
	v_lshl_add_u64 v[2:3], v[2:3], 0, s[78:79]
	v_lshl_add_u64 v[2:3], v[2:3], 0, v[4:5]
	global_load_dwordx4 v[10:13], v[2:3], off offset:1024
	v_lshlrev_b32_e32 v2, 2, v169
	v_add3_u32 v2, s1, v171, v2
	v_add_u32_e32 v3, 0x800, v2
	s_waitcnt vmcnt(6) lgkmcnt(0)
	s_barrier
; #define LAS __attribute__((address_space(3)))
; __device__ __forceinline__ float bflo(unsigned w) { return __uint_as_float(w << 16); }
; __device__ __forceinline__ float bfhi(unsigned w) { return __uint_as_float(w & 0xffff0000u); }
; __device__ __forceinline__ int crow(int r, int hi) { return (r & 3) + 8 * (r >> 2) + 4 * hi; }
; __device__ __forceinline__ unsigned cvtpk(float lo, float hi) { f32x2 v = {lo, hi}; bf16x2_t b = __builtin_convertvector(v, bf16x2_t); return __builtin_bit_cast(unsigned, b); }
; #define ATT_LDS_WAIT() asm volatile("s_waitcnt lgkmcnt(0)" ::: "memory")
; __device__ __forceinline__ float gate8(const f32x4& x0, const f32x4& x1, const float (&gn)[8], const u32x4& zw, bf16* orow) {
;     const float zz[8] = {bflo(zw.x), bfhi(zw.x), bflo(zw.y), bfhi(zw.y), bflo(zw.z), bfhi(zw.z), bflo(zw.w), bfhi(zw.w)};
;     const float xs[8] = {x0[0], x0[1], x0[2], x0[3], x1[0], x1[1], x1[2], x1[3]};
;     float r[8], ssq = 0.f;
; #pragma unroll
;     for (int i = 0; i < 8; ++i) { ssq += xs[i] * xs[i]; r[i] = xs[i] * gn[i] * (zz[i] / (1.0f + __expf(-zz[i]))); }
;     u32x4 w; w.x = cvtpk(r[0], r[1]); w.y = cvtpk(r[2], r[3]); w.z = cvtpk(r[4], r[5]); w.w = cvtpk(r[6], r[7]);
;     *(u32x4*)orow = w;
;     return ssq;
; }
; template <int TYPE>
; __device__ __forceinline__ void prompt_epilogue(const Args& a, int l, int h, size_t rowq  , int col, FoxState& st, const EpiPre& pre, LAS float* wsf, LAS float* stg, int lane, int r32, int hi) {
;     ...
; #pragma unroll
;     for (int r = 0; r < 16; ++r) { stg[crow(r, hi) * 64 + r32] = st.o[0][r]; stg[crow(r, hi) * 64 + 32 + r32] = st.o[1][r]; }
;     ATT_LDS_WAIT();
;     const int ch = lane & 7;
;     const float gn[8] = {pre.g0[0], pre.g0[1], pre.g0[2], pre.g0[3], pre.g1[0], pre.g1[1], pre.g1[2], pre.g1[3]};
; #pragma unroll
;     for (int i = 0; i < 4; ++i) {
;         const int row = i * 8 + (lane >> 3); const size_t grow = rowq + row;
;         const f32x4 x0 = *(const LAS f32x4*)(stg + row * 64 + ch * 8), x1 = *(const LAS f32x4*)(stg + row * 64 + ch * 8 + 4);
;         float ssq = gate8(x0, x1, gn, pre.z[i], (bf16*)(a.ws + WS_HN) + grow * D + col + ch * 8);
;         ssq = sum8_dpp(ssq);
;         if (ch == 0) ((float*)(a.ws + WS_SSQ))[grow * 16 + TYPE * 8 + h] = ssq;
;     }
	ds_write2_b32 v2, v20, v36 offset1:32
	ds_write2_b32 v2, v21, v37 offset0:64 offset1:96
	ds_write2_b32 v2, v22, v38 offset0:128 offset1:160
	ds_write2_b32 v2, v23, v39 offset0:192 offset1:224
	ds_write2_b32 v3, v24, v40 offset1:32
	ds_write2_b32 v3, v25, v41 offset0:64 offset1:96
	ds_write2_b32 v3, v26, v42 offset0:128 offset1:160
	ds_write2_b32 v3, v27, v43 offset0:192 offset1:224
	v_add_u32_e32 v3, 0x1000, v2
	v_add_u32_e32 v2, 0x1800, v2
	ds_write2_b32 v3, v28, v44 offset1:32
	ds_write2_b32 v3, v29, v45 offset0:64 offset1:96
	ds_write2_b32 v3, v30, v46 offset0:128 offset1:160
	ds_write2_b32 v3, v31, v47 offset0:192 offset1:224
	ds_write2_b32 v2, v32, v48 offset1:32
	ds_write2_b32 v2, v33, v49 offset0:64 offset1:96
	ds_write2_b32 v2, v34, v50 offset0:128 offset1:160
	ds_write2_b32 v2, v35, v51 offset0:192 offset1:224
	v_and_b32_e32 v28, 7, v19
	v_lshl_add_u32 v19, v28, 5, s1
	s_waitcnt lgkmcnt(0)
	v_lshl_add_u32 v2, v1, 8, v19
	ds_read_b128 v[30:33], v2
	ds_read_b128 v[20:23], v2 offset:16
	v_lshl_add_u64 v[2:3], s[96:97], 0, v[162:163]
	v_lshl_add_u64 v[2:3], v[2:3], 0, s[78:79]
	v_lshlrev_b32_e32 v4, 4, v28
	v_lshl_add_u64 v[2:3], v[2:3], 0, v[4:5]
	s_waitcnt lgkmcnt(1)
	v_mul_f32_e32 v4, v31, v31
	v_fmac_f32_e32 v4, v30, v30
	v_fmac_f32_e32 v4, v32, v32
	v_fmac_f32_e32 v4, v33, v33
	s_waitcnt lgkmcnt(0)
	v_fmac_f32_e32 v4, v20, v20
	v_fmac_f32_e32 v4, v21, v21
	v_fmac_f32_e32 v4, v22, v22
	v_fmac_f32_e32 v4, v23, v23
	v_cmp_eq_u32_e64 s[6:7], 0, v28
	v_readlane_b32 s9, v242, 13
	s_waitcnt vmcnt(5)
	s_waitcnt vmcnt(0)
	v_pk_mul_f32 v[20:21], v[6:7], v[20:21]
	s_waitcnt vmcnt(4)
	v_pk_mul_f32 v[26:27], v[16:17], v[32:33]
	v_pk_mul_f32 v[30:31], v[14:15], v[30:31]
	s_waitcnt vmcnt(3)
	v_lshlrev_b32_e32 v29, 16, v60
	v_and_b32_e32 v34, 0xffff0000, v60
	v_mul_f32_e32 v24, 0xbfb8aa3b, v29
	v_mul_f32_e32 v25, 0xbfb8aa3b, v34
	v_exp_f32_e32 v24, v24
	v_exp_f32_e32 v25, v25
	v_and_b32_e32 v32, 0xffff0000, v61
	v_pk_add_f32 v[24:25], v[24:25], 1.0 op_sel_hi:[1,0]
	s_nop 0
	v_div_scale_f32 v35, s[2:3], v25, v25, v34
	v_rcp_f32_e32 v36, v35
	s_nop 0
	v_fma_f32 v37, -v35, v36, 1.0
	v_fmac_f32_e32 v36, v37, v36
	v_div_scale_f32 v37, vcc, v34, v25, v34
	v_mul_f32_e32 v38, v37, v36
	v_fma_f32 v39, -v35, v38, v37
	v_fmac_f32_e32 v38, v39, v36
	v_fma_f32 v35, -v35, v38, v37
	v_div_fmas_f32 v35, v35, v36, v38
	v_div_fixup_f32 v25, v35, v25, v34
	v_div_scale_f32 v34, s[2:3], v24, v24, v29
	v_rcp_f32_e32 v35, v34
	s_nop 0
	v_fma_f32 v36, -v34, v35, 1.0
	v_fmac_f32_e32 v35, v36, v35
	v_div_scale_f32 v36, vcc, v29, v24, v29
	v_mul_f32_e32 v37, v36, v35
	v_fma_f32 v38, -v34, v37, v36
	v_fmac_f32_e32 v37, v38, v35
	v_fma_f32 v34, -v34, v37, v36
	v_div_fmas_f32 v34, v34, v35, v37
	v_div_fixup_f32 v24, v34, v24, v29
	v_lshlrev_b32_e32 v29, 16, v61
	v_pk_mul_f32 v[24:25], v[24:25], v[30:31]
	v_mul_f32_e32 v30, 0xbfb8aa3b, v29
	v_mul_f32_e32 v31, 0xbfb8aa3b, v32
	v_exp_f32_e32 v30, v30
	v_exp_f32_e32 v31, v31
	s_nop 0
	v_pk_add_f32 v[30:31], v[30:31], 1.0 op_sel_hi:[1,0]
	s_nop 0
	v_div_scale_f32 v33, s[2:3], v31, v31, v32
	v_rcp_f32_e32 v34, v33
	s_nop 0
	v_fma_f32 v35, -v33, v34, 1.0
	v_fmac_f32_e32 v34, v35, v34
	v_div_scale_f32 v35, vcc, v32, v31, v32
	v_mul_f32_e32 v36, v35, v34
	v_fma_f32 v37, -v33, v36, v35
	v_fmac_f32_e32 v36, v37, v34
	v_fma_f32 v33, -v33, v36, v35
	v_div_fmas_f32 v33, v33, v34, v36
	v_div_fixup_f32 v31, v33, v31, v32
	v_div_scale_f32 v32, s[2:3], v30, v30, v29
	v_rcp_f32_e32 v33, v32
	s_nop 0
	v_fma_f32 v34, -v32, v33, 1.0
	v_fmac_f32_e32 v33, v34, v33
	v_div_scale_f32 v34, vcc, v29, v30, v29
	v_mul_f32_e32 v35, v34, v33
	v_fma_f32 v36, -v32, v35, v34
	v_fmac_f32_e32 v35, v36, v33
	v_fma_f32 v32, -v32, v35, v34
	v_div_fmas_f32 v32, v32, v33, v35
	v_div_fixup_f32 v30, v32, v30, v29
	v_lshlrev_b32_e32 v29, 16, v62
	v_and_b32_e32 v34, 0xffff0000, v62
	v_pk_mul_f32 v[26:27], v[30:31], v[26:27]
	v_mul_f32_e32 v30, 0xbfb8aa3b, v29
	v_mul_f32_e32 v31, 0xbfb8aa3b, v34
	v_exp_f32_e32 v30, v30
	v_exp_f32_e32 v31, v31
	v_pk_mul_f32 v[32:33], v[8:9], v[22:23]
	v_lshlrev_b32_e32 v22, 16, v63
	v_and_b32_e32 v23, 0xffff0000, v63
	v_pk_add_f32 v[30:31], v[30:31], 1.0 op_sel_hi:[1,0]
	s_nop 0
	v_div_scale_f32 v35, s[2:3], v31, v31, v34
	v_rcp_f32_e32 v36, v35
	s_nop 0
	v_fma_f32 v37, -v35, v36, 1.0
	v_fmac_f32_e32 v36, v37, v36
	v_div_scale_f32 v37, vcc, v34, v31, v34
	v_mul_f32_e32 v38, v37, v36
	v_fma_f32 v39, -v35, v38, v37
	v_fmac_f32_e32 v38, v39, v36
	v_fma_f32 v35, -v35, v38, v37
	v_div_fmas_f32 v35, v35, v36, v38
	v_div_fixup_f32 v31, v35, v31, v34
	v_div_scale_f32 v34, s[2:3], v30, v30, v29
	v_rcp_f32_e32 v35, v34
	s_nop 0
	v_fma_f32 v36, -v34, v35, 1.0
	v_fmac_f32_e32 v35, v36, v35
	v_div_scale_f32 v36, vcc, v29, v30, v29
	v_mul_f32_e32 v37, v36, v35
	v_fma_f32 v38, -v34, v37, v36
	v_fmac_f32_e32 v37, v38, v35
	v_fma_f32 v34, -v34, v37, v36
	v_div_fmas_f32 v34, v34, v35, v37
	v_div_fixup_f32 v30, v34, v30, v29
	v_pk_mul_f32 v[30:31], v[30:31], v[20:21]
	v_mul_f32_e32 v20, 0xbfb8aa3b, v22
	v_mul_f32_e32 v21, 0xbfb8aa3b, v23
	v_exp_f32_e32 v20, v20
	v_exp_f32_e32 v21, v21
	s_nop 0
	v_pk_add_f32 v[20:21], v[20:21], 1.0 op_sel_hi:[1,0]
	s_nop 0
	v_div_scale_f32 v29, s[2:3], v21, v21, v23
	v_rcp_f32_e32 v34, v29
	s_nop 0
	v_fma_f32 v35, -v29, v34, 1.0
	v_fmac_f32_e32 v34, v35, v34
	v_div_scale_f32 v35, vcc, v23, v21, v23
	v_mul_f32_e32 v36, v35, v34
	v_fma_f32 v37, -v29, v36, v35
	v_fmac_f32_e32 v36, v37, v34
	v_fma_f32 v29, -v29, v36, v35
	v_div_fmas_f32 v29, v29, v34, v36
	v_div_fixup_f32 v21, v29, v21, v23
	v_div_scale_f32 v23, s[2:3], v20, v20, v22
	v_rcp_f32_e32 v29, v23
	s_nop 0
	v_fma_f32 v34, -v23, v29, 1.0
	v_fmac_f32_e32 v29, v34, v29
	v_div_scale_f32 v34, vcc, v22, v20, v22
	v_mul_f32_e32 v35, v34, v29
	v_fma_f32 v36, -v23, v35, v34
	v_fmac_f32_e32 v35, v36, v29
	v_fma_f32 v23, -v23, v35, v34
	v_div_fmas_f32 v23, v23, v29, v35
	v_div_fixup_f32 v20, v23, v20, v22
	v_pk_mul_f32 v[32:33], v[20:21], v[32:33]
	v_cvt_pk_bf16_f32 v20, v24, v25
	v_cvt_pk_bf16_f32 v21, v26, v27
	v_cvt_pk_bf16_f32 v22, v30, v31
	v_cvt_pk_bf16_f32 v23, v32, v33
	global_store_dwordx4 v[2:3], v[20:23], off offset:1024
	v_add_f32_dpp v2, v4, v4 quad_perm:[1,0,3,2] row_mask:0xf bank_mask:0xf bound_ctrl:1
	v_mov_b32_e32 v3, v5
	s_nop 0
	v_add_f32_dpp v2, v2, v2 quad_perm:[2,3,0,1] row_mask:0xf bank_mask:0xf bound_ctrl:1
	s_nop 1
	v_mov_b32_dpp v3, v2 row_half_mirror row_mask:0xf bank_mask:0xf
	s_and_saveexec_b64 s[2:3], s[6:7]
	v_readlane_b32 s1, v242, 32
	s_cbranch_execz .LBB0_1002
	v_readlane_b32 s8, v242, 36
	v_add_f32_e32 v4, v2, v3
	v_lshlrev_b64 v[2:3], 6, v[160:161]
	v_readlane_b32 s9, v242, 37
	s_nop 1
	v_lshl_add_u64 v[2:3], s[8:9], 0, v[2:3]
	s_lshl_b32 s8, s1, 2
	s_mov_b32 s9, s87
	v_lshl_add_u64 v[2:3], v[2:3], 0, s[8:9]
	global_store_dword v[2:3], v4, off

; #define LAS __attribute__((address_space(3)))
; __device__ __forceinline__ int crow(int r, int hi) { return (r & 3) + 8 * (r >> 2) + 4 * hi; }
; __device__ __forceinline__ float swap_sum(float m) { auto rr = __builtin_amdgcn_permlane32_swap(__float_as_uint(m), __float_as_uint(m), false, false); return __uint_as_float(rr[0]) + __uint_as_float(rr[1]); }
; #define ATT_WAIT_BAR() asm volatile("s_waitcnt vmcnt(0) lgkmcnt(0)\n\ts_barrier" ::: "memory")
; #define ATT_LDS_WAIT() asm volatile("s_waitcnt lgkmcnt(0)" ::: "memory")
; template <int TYPE>
; __device__ __forceinline__ void prompt_epilogue(const Args& a, int l, int h, size_t rowq  , int col, FoxState& st, const EpiPre& pre, LAS float* wsf, LAS float* stg, int lane, int r32, int hi) {
;     if (TYPE == 0) {
;         const float inv = 1.0f / swap_sum(st.l);
;         if (hi == 0) wsf[r32] = inv;
;         ATT_LDS_WAIT();
; #pragma unroll
;         for (int g = 0; g < 4; ++g) { const f32x4 f = *(const LAS f32x4*)(wsf + 8 * g + 4 * hi);
; #pragma unroll
;             for (int i = 0; i < 4; ++i) { st.o[0][4 * g + i] *= f[i]; st.o[1][4 * g + i] *= f[i]; } }
;     }
; #pragma unroll
;     for (int r = 0; r < 16; ++r) { stg[crow(r, hi) * 64 + r32] = st.o[0][r]; stg[crow(r, hi) * 64 + 32 + r32] = st.o[1][r]; }
;     ATT_LDS_WAIT();
;     const int ch = lane & 7;
;     const float gn[8] = {pre.g0[0], pre.g0[1], pre.g0[2], pre.g0[3], pre.g1[0], pre.g1[1], pre.g1[2], pre.g1[3]};
; #pragma unroll
;     for (int i = 0; i < 4; ++i) {
;         const int row = i * 8 + (lane >> 3); const size_t grow = rowq + row;
;         const f32x4 x0 = *(const LAS f32x4*)(stg + row * 64 + ch * 8), x1 = *(const LAS f32x4*)(stg + row * 64 + ch * 8 + 4);
; __device__ __forceinline__ void prompt_unit_fox(const Args& a, int l, int b, int h, int qb, LAS unsigned char* lds) {
;     ...
;     if (pending) fox_pair_pv(st, pp, vp0 + pslot * 16384);
;     EpiPre pre; epi_preload<0>(pre, a, l, h, rowb + q0 + wid * 32, col, lane);
;     ATT_WAIT_BAR();
;     prompt_epilogue<0>(a, l, h, rowb + q0 + wid * 32, col, st, pre, wsf, (LAS float*)lds + wid * 2048, lane, r32, hi);
.LBB0_1012:
	v_readlane_b32 s8, v242, 12
	v_readlane_b32 s9, v242, 13
	s_add_u32 s2, s8, s92
	v_readlane_b32 s94, v242, 38
	s_addc_u32 s3, s9, 0
	v_lshlrev_b32_e32 v2, 2, v178
	v_readlane_b32 s95, v242, 39
	global_load_dwordx4 v[10:13], v2, s[2:3] offset:2064
	global_load_dwordx4 v[14:17], v2, s[2:3] offset:2048
	v_readlane_b32 s2, v242, 47
	v_lshl_add_u64 v[2:3], s[94:95], 0, v[176:177]
	s_mov_b32 s75, s87
	v_readlane_b32 s3, v242, 48
	v_lshl_add_u64 v[2:3], v[2:3], 0, s[74:75]
	v_lshlrev_b32_e32 v4, 1, v178
	v_lshl_add_u64 v[6:7], s[2:3], 0, v[176:177]
	v_readlane_b32 s2, v237, 9
	v_lshl_add_u64 v[2:3], v[2:3], 0, v[4:5]
	v_lshl_add_u64 v[6:7], v[6:7], 0, s[74:75]
	v_readlane_b32 s3, v237, 10
	v_lshl_add_u64 v[6:7], v[6:7], 0, v[4:5]
	global_load_dwordx4 v[28:31], v[2:3], off
	global_load_dwordx4 v[24:27], v[6:7], off
	v_lshl_add_u64 v[2:3], s[2:3], 0, v[176:177]
	v_readlane_b32 s2, v237, 5
	v_readlane_b32 s3, v237, 6
	v_lshl_add_u64 v[2:3], v[2:3], 0, s[74:75]
	v_lshl_add_u64 v[2:3], v[2:3], 0, v[4:5]
	v_lshl_add_u64 v[6:7], s[2:3], 0, v[176:177]
	v_lshl_add_u64 v[6:7], v[6:7], 0, s[74:75]
	v_lshl_add_u64 v[6:7], v[6:7], 0, v[4:5]
	global_load_dwordx4 v[20:23], v[2:3], off
	s_nop 0
	global_load_dwordx4 v[6:9], v[6:7], off
	s_waitcnt vmcnt(6) lgkmcnt(0)
	s_barrier
	v_readlane_b32 s76, v237, 3
	v_readlane_b32 s96, v242, 30
	v_mov_b32_e32 v2, v194
	v_readlane_b32 s77, v237, 4
	v_readlane_b32 s97, v242, 31
	v_readlane_b32 s12, v242, 32
	v_readlane_b32 s13, v242, 34
	v_permlane32_swap_b32_e32 v194, v2
	v_readlane_b32 s10, v242, 14
	v_readlane_b32 s11, v242, 15
	s_and_saveexec_b64 s[2:3], s[6:7]
	s_cbranch_execz .LBB0_1014
	v_add_f32_e32 v2, v194, v2
	v_div_scale_f32 v3, s[6:7], v2, v2, 1.0
	v_rcp_f32_e32 v4, v3
	v_div_scale_f32 v32, vcc, 1.0, v2, 1.0
	v_fma_f32 v33, -v3, v4, 1.0
	v_fmac_f32_e32 v4, v33, v4
	v_mul_f32_e32 v33, v32, v4
	v_fma_f32 v34, -v3, v33, v32
	v_fmac_f32_e32 v33, v34, v4
	v_fma_f32 v3, -v3, v33, v32
	v_div_fmas_f32 v3, v3, v4, v33
	v_div_fixup_f32 v2, v3, v2, 1.0
	ds_write_b32 v184, v2
.LBB0_1014:
	s_or_b64 exec, exec, s[2:3]
	s_waitcnt lgkmcnt(0)
	v_add_u32_e32 v2, s89, v174
	ds_read_b128 v[32:35], v2
	ds_read_b128 v[36:39], v2 offset:32
	s_lshl_b32 s0, s1, 13
	s_add_i32 s0, s0, 0
	s_waitcnt lgkmcnt(1)
	v_mul_f32_e32 v3, v68, v32
	v_mul_f32_e32 v4, v52, v32
	v_mul_f32_e32 v40, v69, v33
	v_mul_f32_e32 v41, v53, v33
	v_mul_f32_e32 v42, v70, v34
	v_mul_f32_e32 v43, v54, v34
	v_mul_f32_e32 v44, v71, v35
	v_mul_f32_e32 v45, v55, v35
	ds_read_b128 v[32:35], v2 offset:64
	s_waitcnt lgkmcnt(1)
	v_mul_f32_e32 v46, v72, v36
	v_mul_f32_e32 v47, v56, v36
	v_mul_f32_e32 v48, v73, v37
	v_mul_f32_e32 v49, v57, v37
	v_mul_f32_e32 v50, v74, v38
	v_mul_f32_e32 v51, v58, v38
	v_mul_f32_e32 v52, v75, v39
	v_mul_f32_e32 v53, v59, v39
	ds_read_b128 v[36:39], v2 offset:96
	s_waitcnt lgkmcnt(1)
	v_mul_f32_e32 v54, v77, v33
	v_mul_f32_e32 v33, v61, v33
	v_lshlrev_b32_e32 v61, 2, v180
	v_add3_u32 v61, s0, v182, v61
	ds_write2_b32 v61, v3, v4 offset1:32
	ds_write2_b32 v61, v40, v41 offset0:64 offset1:96
	ds_write2_b32 v61, v42, v43 offset0:128 offset1:160
	ds_write2_b32 v61, v44, v45 offset0:192 offset1:224
	v_add_u32_e32 v3, 0x800, v61
	v_mul_f32_e32 v2, v76, v32
	v_mul_f32_e32 v32, v60, v32
	ds_write2_b32 v3, v46, v47 offset1:32
	ds_write2_b32 v3, v48, v49 offset0:64 offset1:96
	ds_write2_b32 v3, v50, v51 offset0:128 offset1:160
	ds_write2_b32 v3, v52, v53 offset0:192 offset1:224
	v_add_u32_e32 v3, 0x1000, v61
	v_mul_f32_e32 v55, v78, v34
	v_mul_f32_e32 v34, v62, v34
	v_mul_f32_e32 v56, v79, v35
	v_mul_f32_e32 v35, v63, v35
	s_waitcnt lgkmcnt(8)
	v_mul_f32_e32 v57, v80, v36
	v_mul_f32_e32 v36, v64, v36
	ds_write2_b32 v3, v2, v32 offset1:32
	ds_write2_b32 v3, v54, v33 offset0:64 offset1:96
	ds_write2_b32 v3, v55, v34 offset0:128 offset1:160
	ds_write2_b32 v3, v56, v35 offset0:192 offset1:224
	v_add_u32_e32 v2, 0x1800, v61
	v_mul_f32_e32 v58, v81, v37
	v_mul_f32_e32 v37, v65, v37
	v_mul_f32_e32 v59, v82, v38
	v_mul_f32_e32 v38, v66, v38
	v_mul_f32_e32 v60, v83, v39
	v_mul_f32_e32 v39, v67, v39
	ds_write2_b32 v2, v57, v36 offset1:32
	ds_write2_b32 v2, v58, v37 offset0:64 offset1:96
	ds_write2_b32 v2, v59, v38 offset0:128 offset1:160
	ds_write2_b32 v2, v60, v39 offset0:192 offset1:224
	v_and_b32_e32 v2, 7, v19
	v_lshl_add_u32 v19, v2, 5, s0
	s_waitcnt lgkmcnt(0)
	v_lshl_add_u32 v3, v1, 8, v19
	ds_read_b128 v[32:35], v3
	ds_read_b128 v[36:39], v3 offset:16
	s_waitcnt vmcnt(3)
	s_waitcnt vmcnt(0)
	v_lshlrev_b32_e32 v3, 16, v28
	v_and_b32_e32 v28, 0xffff0000, v28
	v_mul_f32_e32 v4, 0xbfb8aa3b, v3
	v_exp_f32_e32 v42, v4
	v_mul_f32_e32 v4, 0xbfb8aa3b, v28
	v_exp_f32_e32 v43, v4
	v_lshl_add_u64 v[40:41], s[96:97], 0, v[176:177]
	v_lshl_add_u64 v[40:41], v[40:41], 0, s[74:75]
	v_lshlrev_b32_e32 v4, 4, v2
	v_pk_add_f32 v[42:43], v[42:43], 1.0 op_sel_hi:[1,0]
	v_lshl_add_u64 v[40:41], v[40:41], 0, v[4:5]
	v_div_scale_f32 v46, s[0:1], v43, v43, v28
	v_rcp_f32_e32 v47, v46
	s_waitcnt lgkmcnt(1)
; #define LAS __attribute__((address_space(3)))
; __device__ __forceinline__ float bflo(unsigned w) { return __uint_as_float(w << 16); }
; __device__ __forceinline__ float bfhi(unsigned w) { return __uint_as_float(w & 0xffff0000u); }
; __device__ __forceinline__ unsigned cvtpk(float lo, float hi) { f32x2 v = {lo, hi}; bf16x2_t b = __builtin_convertvector(v, bf16x2_t); return __builtin_bit_cast(unsigned, b); }
; __device__ __forceinline__ float gate8(const f32x4& x0, const f32x4& x1, const float (&gn)[8], const u32x4& zw, bf16* orow) {
;     const float zz[8] = {bflo(zw.x), bfhi(zw.x), bflo(zw.y), bfhi(zw.y), bflo(zw.z), bfhi(zw.z), bflo(zw.w), bfhi(zw.w)};
;     const float xs[8] = {x0[0], x0[1], x0[2], x0[3], x1[0], x1[1], x1[2], x1[3]};
;     float r[8], ssq = 0.f;
; #pragma unroll
;     for (int i = 0; i < 8; ++i) { ssq += xs[i] * xs[i]; r[i] = xs[i] * gn[i] * (zz[i] / (1.0f + __expf(-zz[i]))); }
;     u32x4 w; w.x = cvtpk(r[0], r[1]); w.y = cvtpk(r[2], r[3]); w.z = cvtpk(r[4], r[5]); w.w = cvtpk(r[6], r[7]);
;     *(u32x4*)orow = w;
;     return ssq;
; }
; template <int TYPE>
; __device__ __forceinline__ void prompt_epilogue(const Args& a, int l, int h, size_t rowq  , int col, FoxState& st, const EpiPre& pre, LAS float* wsf, LAS float* stg, int lane, int r32, int hi) {
;     ...
;     for (int i = 0; i < 4; ++i) {
;         const int row = i * 8 + (lane >> 3); const size_t grow = rowq + row;
;         const f32x4 x0 = *(const LAS f32x4*)(stg + row * 64 + ch * 8), x1 = *(const LAS f32x4*)(stg + row * 64 + ch * 8 + 4);
;         float ssq = gate8(x0, x1, gn, pre.z[i], (bf16*)(a.ws + WS_HN) + grow * D + col + ch * 8);
;         ssq = sum8_dpp(ssq);
;         if (ch == 0) ((float*)(a.ws + WS_SSQ))[grow * 16 + TYPE * 8 + h] = ssq;
;     }
	v_mul_f32_e32 v4, v33, v33
	v_fmac_f32_e32 v4, v32, v32
	v_pk_mul_f32 v[44:45], v[16:17], v[34:35]
	v_fma_f32 v48, -v46, v47, 1.0
	v_fmac_f32_e32 v47, v48, v47
	v_div_scale_f32 v48, vcc, v28, v43, v28
	v_mul_f32_e32 v49, v48, v47
	v_fma_f32 v50, -v46, v49, v48
	v_fmac_f32_e32 v49, v50, v47
	v_fma_f32 v46, -v46, v49, v48
	v_div_scale_f32 v48, s[0:1], v42, v42, v3
	v_rcp_f32_e32 v50, v48
	v_div_fmas_f32 v46, v46, v47, v49
	v_div_fixup_f32 v43, v46, v43, v28
	v_and_b32_e32 v49, 0xffff0000, v29
	v_fma_f32 v28, -v48, v50, 1.0
	v_fmac_f32_e32 v50, v28, v50
	v_div_scale_f32 v28, vcc, v3, v42, v3
	v_mul_f32_e32 v46, v28, v50
	v_fma_f32 v47, -v48, v46, v28
	v_fmac_f32_e32 v46, v47, v50
	v_fma_f32 v47, -v48, v46, v28
	v_lshlrev_b32_e32 v48, 16, v29
	v_mul_f32_e32 v28, 0xbfb8aa3b, v48
	v_mul_f32_e32 v29, 0xbfb8aa3b, v49
	v_exp_f32_e32 v28, v28
	v_exp_f32_e32 v29, v29
	v_div_fmas_f32 v46, v47, v50, v46
	v_div_fixup_f32 v42, v46, v42, v3
	v_fmac_f32_e32 v4, v34, v34
	v_pk_add_f32 v[28:29], v[28:29], 1.0 op_sel_hi:[1,0]
	v_pk_mul_f32 v[32:33], v[14:15], v[32:33]
	v_div_scale_f32 v3, s[0:1], v29, v29, v49
	v_rcp_f32_e32 v46, v3
	v_fmac_f32_e32 v4, v35, v35
	v_pk_mul_f32 v[32:33], v[42:43], v[32:33]
	s_waitcnt lgkmcnt(0)
	v_fmac_f32_e32 v4, v36, v36
	v_fma_f32 v34, -v3, v46, 1.0
	v_fmac_f32_e32 v46, v34, v46
	v_div_scale_f32 v34, vcc, v49, v29, v49
	v_mul_f32_e32 v35, v34, v46
	v_fma_f32 v42, -v3, v35, v34
	v_fmac_f32_e32 v35, v42, v46
	v_fma_f32 v3, -v3, v35, v34
	v_div_scale_f32 v34, s[0:1], v28, v28, v48
	v_rcp_f32_e32 v42, v34
	v_div_fmas_f32 v3, v3, v46, v35
	v_div_fixup_f32 v29, v3, v29, v49
	v_lshlrev_b32_e32 v46, 16, v30
	v_fma_f32 v3, -v34, v42, 1.0
	v_fmac_f32_e32 v42, v3, v42
	v_div_scale_f32 v3, vcc, v48, v28, v48
	v_mul_f32_e32 v35, v3, v42
	v_fma_f32 v43, -v34, v35, v3
	v_fmac_f32_e32 v35, v43, v42
	v_fma_f32 v3, -v34, v35, v3
	v_and_b32_e32 v30, 0xffff0000, v30
	v_div_fmas_f32 v3, v3, v42, v35
	v_mul_f32_e32 v34, 0xbfb8aa3b, v46
	v_mul_f32_e32 v35, 0xbfb8aa3b, v30
	v_exp_f32_e32 v34, v34
	v_exp_f32_e32 v35, v35
	v_div_fixup_f32 v28, v3, v28, v48
	v_pk_mul_f32 v[42:43], v[28:29], v[44:45]
	v_fmac_f32_e32 v4, v37, v37
	v_pk_add_f32 v[28:29], v[34:35], 1.0 op_sel_hi:[1,0]
	v_pk_mul_f32 v[36:37], v[10:11], v[36:37]
	v_div_scale_f32 v3, s[0:1], v29, v29, v30
	v_rcp_f32_e32 v44, v3
	v_pk_mul_f32 v[34:35], v[12:13], v[38:39]
	v_fmac_f32_e32 v4, v38, v38
	v_fmac_f32_e32 v4, v39, v39
	v_fma_f32 v45, -v3, v44, 1.0
	v_fmac_f32_e32 v44, v45, v44
	v_div_scale_f32 v45, vcc, v30, v29, v30
	v_mul_f32_e32 v47, v45, v44
	v_fma_f32 v48, -v3, v47, v45
	v_fmac_f32_e32 v47, v48, v44
	v_fma_f32 v3, -v3, v47, v45
	v_div_scale_f32 v45, s[0:1], v28, v28, v46
	v_rcp_f32_e32 v48, v45
	v_div_fmas_f32 v3, v3, v44, v47
	v_div_fixup_f32 v29, v3, v29, v30
	v_and_b32_e32 v47, 0xffff0000, v31
	v_fma_f32 v3, -v45, v48, 1.0
	v_fmac_f32_e32 v48, v3, v48
	v_div_scale_f32 v3, vcc, v46, v28, v46
	v_mul_f32_e32 v44, v3, v48
	v_fma_f32 v30, -v45, v44, v3
	v_fmac_f32_e32 v44, v30, v48
	v_fma_f32 v3, -v45, v44, v3
	v_lshlrev_b32_e32 v45, 16, v31
	v_mul_f32_e32 v30, 0xbfb8aa3b, v45
	v_mul_f32_e32 v31, 0xbfb8aa3b, v47
	v_exp_f32_e32 v30, v30
	v_exp_f32_e32 v31, v31
	v_div_fmas_f32 v3, v3, v48, v44
	v_div_fixup_f32 v28, v3, v28, v46
	v_pk_mul_f32 v[36:37], v[28:29], v[36:37]
	v_pk_add_f32 v[30:31], v[30:31], 1.0 op_sel_hi:[1,0]
	v_cmp_eq_u32_e64 s[6:7], 0, v2
	v_div_scale_f32 v3, s[0:1], v31, v31, v47
	v_rcp_f32_e32 v44, v3
	s_nop 0
	v_fma_f32 v28, -v3, v44, 1.0
	v_fmac_f32_e32 v44, v28, v44
	v_div_scale_f32 v28, vcc, v47, v31, v47
	v_mul_f32_e32 v29, v28, v44
	v_fma_f32 v38, -v3, v29, v28
	v_fmac_f32_e32 v29, v38, v44
	v_fma_f32 v3, -v3, v29, v28
	v_div_scale_f32 v28, s[0:1], v30, v30, v45
	v_rcp_f32_e32 v38, v28
	v_div_fmas_f32 v3, v3, v44, v29
	v_div_fixup_f32 v29, v3, v31, v47
	v_fma_f32 v3, -v28, v38, 1.0
	v_fmac_f32_e32 v38, v3, v38
	v_div_scale_f32 v3, vcc, v45, v30, v45
	v_mul_f32_e32 v31, v3, v38
	v_fma_f32 v39, -v28, v31, v3
	v_fmac_f32_e32 v31, v39, v38
	v_fma_f32 v3, -v28, v31, v3
	v_div_fmas_f32 v3, v3, v38, v31
	v_div_fixup_f32 v28, v3, v30, v45
	v_pk_mul_f32 v[34:35], v[28:29], v[34:35]
	v_add_f32_dpp v3, v4, v4 quad_perm:[1,0,3,2] row_mask:0xf bank_mask:0xf bound_ctrl:1
	v_mov_b32_e32 v4, v5
	v_cvt_pk_bf16_f32 v28, v32, v33
	v_add_f32_dpp v3, v3, v3 quad_perm:[2,3,0,1] row_mask:0xf bank_mask:0xf bound_ctrl:1
	v_cvt_pk_bf16_f32 v29, v42, v43
	v_cvt_pk_bf16_f32 v30, v36, v37
	v_cvt_pk_bf16_f32 v31, v34, v35
	v_mov_b32_dpp v4, v3 row_half_mirror row_mask:0xf bank_mask:0xf
	global_store_dwordx4 v[40:41], v[28:31], off
	s_and_saveexec_b64 s[2:3], s[6:7]
	s_cbranch_execz .LBB0_1016
	v_readlane_b32 s0, v237, 7
	v_lshlrev_b64 v[28:29], 6, v[168:169]
	v_readlane_b32 s1, v237, 8
	v_add_f32_e32 v3, v3, v4
	s_nop 0
	v_lshl_add_u64 v[28:29], s[0:1], 0, v[28:29]
	s_lshl_b32 s0, s12, 2
	s_mov_b32 s1, s87
	v_lshl_add_u64 v[28:29], v[28:29], 0, s[0:1]
	global_store_dword v[28:29], v3, off

; __device__ __forceinline__ float bflo(unsigned w) { return __uint_as_float(w << 16); }
; __device__ __forceinline__ float bfhi(unsigned w) { return __uint_as_float(w & 0xffff0000u); }
;     __device__ __forceinline__ void begin(const pg8::Unit& u, int ui) const {
;     ...
;             const float* sq = ssq + (size_t)(u.pm * 256 + tid) * 16;
;             const pg8::f32x4 a0 = *(const pg8::f32x4*)sq, a1 = *(const pg8::f32x4*)(sq + 4), b0 = *(const pg8::f32x4*)(sq + 8), b1 = *(const pg8::f32x4*)(sq + 12);
;     __device__ __forceinline__ void operator()(const pg8::f32x4 (&acc)[2][2][4][2], const pg8::Unit& u, int ui, int wr, int wc, int fr, int fq) const {
;     ...
;             for (int m = 0; m < 4; ++m) { const size_t ro = off0 + (size_t)(ai * 128 + m * 16) * D;
; #pragma unroll
;                 for (int bj = 0; bj < 2; ++bj) {
;                     if (l == 0) { x[m][bj][0] = *(const pg8::f32x4*)(xin_p + ro + bj * 128); x[m][bj][1] = *(const pg8::f32x4*)(xin_p + ro + bj * 128 + 4); }
;                     else { const u32x4 w = *(const u32x4*)(xb + ro + bj * 128);
;                            x[m][bj][0] = (pg8::f32x4){bflo(w.x), bfhi(w.x), bflo(w.y), bfhi(w.y)}; x[m][bj][1] = (pg8::f32x4){bflo(w.z), bfhi(w.z), bflo(w.w), bfhi(w.w)}; } } }
.LBB0_1309:
	s_and_saveexec_b64 s[94:95], s[4:5]
	v_lshl_or_b32 v234, s20, 8, v0
	v_ashrrev_i32_e32 v235, 31, v234
	v_lshlrev_b64 v[234:235], 6, v[234:235]
	v_lshl_add_u64 v[234:235], s[10:11], 0, v[234:235]
	global_load_dwordx4 v[238:241], v[234:235], off
	global_load_dwordx4 v[244:247], v[234:235], off offset:16
	global_load_dwordx4 v[248:251], v[234:235], off offset:32
	global_load_dwordx4 v[252:255], v[234:235], off offset:48
	s_mov_b64 exec, s[94:95]
	s_nop 1
	s_lshl_b32 s2, s58, 8
	s_ashr_i32 s25, s24, 31
	s_ashr_i32 s3, s2, 31
	v_lshl_add_u64 v[4:5], s[2:3], 1, v[148:149]
	s_lshl_b64 s[2:3], s[24:25], 19
	v_lshl_add_u64 v[4:5], v[4:5], 0, s[2:3]
	global_load_dwordx4 v[168:171], v[4:5], off
	global_load_dwordx4 v[172:175], v[4:5], off offset:256
	v_add_co_u32_e32 v162, vcc, s48, v4
	s_add_i32 s2, 0, 0x20400
	s_nop 0
	v_addc_co_u32_e32 v163, vcc, 0, v5, vcc
	global_load_dwordx4 v[176:179], v[162:163], off
	global_load_dwordx4 v[180:183], v[162:163], off offset:256
	v_add_co_u32_e32 v160, vcc, s44, v4
	v_add_u32_e32 v3, s2, v166
	s_nop 0
	v_addc_co_u32_e32 v161, vcc, 0, v5, vcc
	global_load_dwordx4 v[184:187], v[160:161], off
	global_load_dwordx4 v[188:191], v[160:161], off offset:256
	v_add_co_u32_e32 v158, vcc, s47, v4
	s_mov_b64 s[2:3], -1
	s_nop 0
	v_addc_co_u32_e32 v159, vcc, 0, v5, vcc
	global_load_dwordx4 v[192:195], v[158:159], off
	global_load_dwordx4 v[134:137], v[158:159], off offset:256
	ds_read_b32 v166, v3 offset:4

; __device__ __forceinline__ float bflo(unsigned w) { return __uint_as_float(w << 16); }
; __device__ __forceinline__ float bfhi(unsigned w) { return __uint_as_float(w & 0xffff0000u); }
; __device__ __forceinline__ unsigned cvt_pk_bf16(float lo, float hi) { unsigned r; asm volatile("v_cvt_pk_bf16_f32 %0, %1, %2" : "=v"(r) : "v"(lo), "v"(hi)); return r; }
;     __device__ __forceinline__ void operator()(const pg8::f32x4 (&acc)[2][2][4][2], const pg8::Unit& u, int ui, int wr, int wc, int fr, int fq) const {
;     ...
;             for (int m = 0; m < 4; ++m) { const size_t ro = off0 + (size_t)(ai * 128 + m * 16) * D;
; #pragma unroll
;                 for (int bj = 0; bj < 2; ++bj) {
;                     if (l == 0) { x[m][bj][0] = *(const pg8::f32x4*)(xin_p + ro + bj * 128); x[m][bj][1] = *(const pg8::f32x4*)(xin_p + ro + bj * 128 + 4); }
;                     else { const u32x4 w = *(const u32x4*)(xb + ro + bj * 128);
;                            x[m][bj][0] = (pg8::f32x4){bflo(w.x), bfhi(w.x), bflo(w.y), bfhi(w.y)}; x[m][bj][1] = (pg8::f32x4){bflo(w.z), bfhi(w.z), bflo(w.w), bfhi(w.w)}; } } }
; #pragma unroll
;             for (int m = 0; m < 4; ++m) { const size_t ro = off0 + (size_t)(ai * 128 + m * 16) * D; const float rB = tb[(ai * 128 + m * 16) * 2];
; #pragma unroll
;                 for (int bj = 0; bj < 2; ++bj) {
;                     const pg8::f32x4 y0 = x[m][bj][0] + acc[ai][bj][m][0] * rB, y1 = x[m][bj][1] + acc[ai][bj][m][1] * rB;
;                     u32x4 o; o.x = pg8::cvt_pk_bf16(y0[0], y0[1]); o.y = pg8::cvt_pk_bf16(y0[2], y0[3]); o.z = pg8::cvt_pk_bf16(y1[0], y1[1]); o.w = pg8::cvt_pk_bf16(y1[2], y1[3]);
;                     *(u32x4*)(xb + ro + bj * 128) = o; } }
	s_waitcnt vmcnt(7)
	v_lshlrev_b32_e32 v196, 16, v168
	v_and_b32_e32 v197, 0xffff0000, v168
	v_lshlrev_b32_e32 v168, 16, v169
	v_and_b32_e32 v169, 0xffff0000, v169
	v_lshlrev_b32_e32 v198, 16, v170
	v_and_b32_e32 v199, 0xffff0000, v170
	v_lshlrev_b32_e32 v170, 16, v171
	v_and_b32_e32 v171, 0xffff0000, v171
	s_waitcnt vmcnt(6)
	v_lshlrev_b32_e32 v200, 16, v172
	v_and_b32_e32 v201, 0xffff0000, v172
	v_lshlrev_b32_e32 v202, 16, v174
	v_and_b32_e32 v203, 0xffff0000, v174
	v_lshlrev_b32_e32 v174, 16, v175
	v_and_b32_e32 v175, 0xffff0000, v175
	s_waitcnt lgkmcnt(0)
	v_pk_fma_f32 v[132:133], v[132:133], v[166:167], v[168:169] op_sel_hi:[1,0,1]
	v_pk_fma_f32 v[130:131], v[130:131], v[166:167], v[196:197] op_sel_hi:[1,0,1]
	v_pk_fma_f32 v[168:169], v[128:129], v[166:167], v[170:171] op_sel_hi:[1,0,1]
	v_pk_fma_f32 v[128:129], v[126:127], v[166:167], v[198:199] op_sel_hi:[1,0,1]
	v_cvt_pk_bf16_f32 v126, v130, v131
	v_cvt_pk_bf16_f32 v127, v132, v133
	v_lshlrev_b32_e32 v172, 16, v173
	v_and_b32_e32 v173, 0xffff0000, v173
	v_cvt_pk_bf16_f32 v128, v128, v129
	v_cvt_pk_bf16_f32 v129, v168, v169
	global_store_dwordx4 v[4:5], v[126:129], off
	v_pk_fma_f32 v[122:123], v[122:123], v[166:167], v[200:201] op_sel_hi:[1,0,1]
	v_pk_fma_f32 v[124:125], v[124:125], v[166:167], v[172:173] op_sel_hi:[1,0,1]
	v_pk_fma_f32 v[126:127], v[120:121], v[166:167], v[174:175] op_sel_hi:[1,0,1]
	v_pk_fma_f32 v[120:121], v[118:119], v[166:167], v[202:203] op_sel_hi:[1,0,1]
	v_cvt_pk_bf16_f32 v118, v122, v123
	v_cvt_pk_bf16_f32 v119, v124, v125
	s_waitcnt vmcnt(6)
	v_lshlrev_b32_e32 v204, 16, v176
	v_cvt_pk_bf16_f32 v120, v120, v121
	v_cvt_pk_bf16_f32 v121, v126, v127
	ds_read_b32 v122, v3 offset:132
	v_and_b32_e32 v205, 0xffff0000, v176
	v_lshlrev_b32_e32 v176, 16, v177
	v_and_b32_e32 v177, 0xffff0000, v177
	v_lshlrev_b32_e32 v206, 16, v178
	v_and_b32_e32 v207, 0xffff0000, v178
	v_lshlrev_b32_e32 v178, 16, v179
	v_and_b32_e32 v179, 0xffff0000, v179
	s_waitcnt vmcnt(5)
	v_lshlrev_b32_e32 v208, 16, v180
	v_and_b32_e32 v209, 0xffff0000, v180
	v_lshlrev_b32_e32 v210, 16, v182
	v_and_b32_e32 v211, 0xffff0000, v182
	v_lshlrev_b32_e32 v182, 16, v183
	v_and_b32_e32 v183, 0xffff0000, v183
	global_store_dwordx4 v[4:5], v[118:121], off offset:256
	s_waitcnt lgkmcnt(0)
	v_pk_fma_f32 v[116:117], v[116:117], v[122:123], v[176:177] op_sel_hi:[1,0,1]
	v_pk_fma_f32 v[114:115], v[114:115], v[122:123], v[204:205] op_sel_hi:[1,0,1]
	v_pk_fma_f32 v[118:119], v[112:113], v[122:123], v[178:179] op_sel_hi:[1,0,1]
	v_pk_fma_f32 v[112:113], v[110:111], v[122:123], v[206:207] op_sel_hi:[1,0,1]
	v_cvt_pk_bf16_f32 v110, v114, v115
	v_cvt_pk_bf16_f32 v111, v116, v117
	v_lshlrev_b32_e32 v180, 16, v181
	v_and_b32_e32 v181, 0xffff0000, v181
	v_cvt_pk_bf16_f32 v112, v112, v113
	v_cvt_pk_bf16_f32 v113, v118, v119
	global_store_dwordx4 v[162:163], v[110:113], off
	v_pk_fma_f32 v[106:107], v[106:107], v[122:123], v[208:209] op_sel_hi:[1,0,1]
	v_pk_fma_f32 v[108:109], v[108:109], v[122:123], v[180:181] op_sel_hi:[1,0,1]
	v_pk_fma_f32 v[110:111], v[104:105], v[122:123], v[182:183] op_sel_hi:[1,0,1]
	v_pk_fma_f32 v[104:105], v[102:103], v[122:123], v[210:211] op_sel_hi:[1,0,1]
	v_cvt_pk_bf16_f32 v102, v106, v107
	v_cvt_pk_bf16_f32 v103, v108, v109
	s_waitcnt vmcnt(6)
	v_lshlrev_b32_e32 v212, 16, v184
	v_cvt_pk_bf16_f32 v104, v104, v105
	v_cvt_pk_bf16_f32 v105, v110, v111
	ds_read_b32 v106, v3 offset:260
	v_and_b32_e32 v213, 0xffff0000, v184
	v_lshlrev_b32_e32 v184, 16, v185
	v_and_b32_e32 v185, 0xffff0000, v185
	v_lshlrev_b32_e32 v214, 16, v186
	v_and_b32_e32 v215, 0xffff0000, v186
	v_lshlrev_b32_e32 v186, 16, v187
	v_and_b32_e32 v187, 0xffff0000, v187
	s_waitcnt vmcnt(5)
	v_lshlrev_b32_e32 v216, 16, v188
	v_and_b32_e32 v217, 0xffff0000, v188
	v_lshlrev_b32_e32 v218, 16, v190
	v_and_b32_e32 v219, 0xffff0000, v190
	v_lshlrev_b32_e32 v190, 16, v191
	v_and_b32_e32 v191, 0xffff0000, v191
	global_store_dwordx4 v[162:163], v[102:105], off offset:256
	s_waitcnt lgkmcnt(0)
	v_pk_fma_f32 v[100:101], v[100:101], v[106:107], v[184:185] op_sel_hi:[1,0,1]
	v_pk_fma_f32 v[98:99], v[98:99], v[106:107], v[212:213] op_sel_hi:[1,0,1]
	v_pk_fma_f32 v[102:103], v[96:97], v[106:107], v[186:187] op_sel_hi:[1,0,1]
	v_pk_fma_f32 v[96:97], v[94:95], v[106:107], v[214:215] op_sel_hi:[1,0,1]
	v_cvt_pk_bf16_f32 v94, v98, v99
	v_cvt_pk_bf16_f32 v95, v100, v101
	v_lshlrev_b32_e32 v188, 16, v189
	v_and_b32_e32 v189, 0xffff0000, v189
	v_cvt_pk_bf16_f32 v96, v96, v97
	v_cvt_pk_bf16_f32 v97, v102, v103
	global_store_dwordx4 v[160:161], v[94:97], off
	v_pk_fma_f32 v[90:91], v[90:91], v[106:107], v[216:217] op_sel_hi:[1,0,1]
	v_pk_fma_f32 v[92:93], v[92:93], v[106:107], v[188:189] op_sel_hi:[1,0,1]
	v_pk_fma_f32 v[94:95], v[88:89], v[106:107], v[190:191] op_sel_hi:[1,0,1]
	v_pk_fma_f32 v[88:89], v[86:87], v[106:107], v[218:219] op_sel_hi:[1,0,1]
	v_cvt_pk_bf16_f32 v86, v90, v91
	v_cvt_pk_bf16_f32 v87, v92, v93
	s_waitcnt vmcnt(6)
	v_lshlrev_b32_e32 v220, 16, v192
	v_cvt_pk_bf16_f32 v88, v88, v89
	v_cvt_pk_bf16_f32 v89, v94, v95
	ds_read_b32 v90, v3 offset:388
	v_and_b32_e32 v221, 0xffff0000, v192
	v_lshlrev_b32_e32 v192, 16, v193
	v_and_b32_e32 v193, 0xffff0000, v193
	v_lshlrev_b32_e32 v222, 16, v194
	v_and_b32_e32 v223, 0xffff0000, v194
	v_lshlrev_b32_e32 v194, 16, v195
	v_and_b32_e32 v195, 0xffff0000, v195
	s_waitcnt vmcnt(5)
	v_lshlrev_b32_e32 v110, 16, v136
	v_and_b32_e32 v111, 0xffff0000, v136
	v_lshlrev_b32_e32 v92, 16, v137
	v_and_b32_e32 v93, 0xffff0000, v137
	global_store_dwordx4 v[160:161], v[86:89], off offset:256
	s_waitcnt lgkmcnt(0)
; __device__ __forceinline__ float bflo(unsigned w) { return __uint_as_float(w << 16); }
; __device__ __forceinline__ float bfhi(unsigned w) { return __uint_as_float(w & 0xffff0000u); }
; __device__ __forceinline__ unsigned cvt_pk_bf16(float lo, float hi) { unsigned r; asm volatile("v_cvt_pk_bf16_f32 %0, %1, %2" : "=v"(r) : "v"(lo), "v"(hi)); return r; }
;     __device__ __forceinline__ void operator()(const pg8::f32x4 (&acc)[2][2][4][2], const pg8::Unit& u, int ui, int wr, int wc, int fr, int fq) const {
;     ...
;             for (int m = 0; m < 4; ++m) { const size_t ro = off0 + (size_t)(ai * 128 + m * 16) * D;
; #pragma unroll
;                 for (int bj = 0; bj < 2; ++bj) {
;                     if (l == 0) { x[m][bj][0] = *(const pg8::f32x4*)(xin_p + ro + bj * 128); x[m][bj][1] = *(const pg8::f32x4*)(xin_p + ro + bj * 128 + 4); }
;                     else { const u32x4 w = *(const u32x4*)(xb + ro + bj * 128);
;                            x[m][bj][0] = (pg8::f32x4){bflo(w.x), bfhi(w.x), bflo(w.y), bfhi(w.y)}; x[m][bj][1] = (pg8::f32x4){bflo(w.z), bfhi(w.z), bflo(w.w), bfhi(w.w)}; } } }
; #pragma unroll
;             for (int m = 0; m < 4; ++m) { const size_t ro = off0 + (size_t)(ai * 128 + m * 16) * D; const float rB = tb[(ai * 128 + m * 16) * 2];
; #pragma unroll
;                 for (int bj = 0; bj < 2; ++bj) {
;                     const pg8::f32x4 y0 = x[m][bj][0] + acc[ai][bj][m][0] * rB, y1 = x[m][bj][1] + acc[ai][bj][m][1] * rB;
;                     u32x4 o; o.x = pg8::cvt_pk_bf16(y0[0], y0[1]); o.y = pg8::cvt_pk_bf16(y0[2], y0[3]); o.z = pg8::cvt_pk_bf16(y1[0], y1[1]); o.w = pg8::cvt_pk_bf16(y1[2], y1[3]);
;                     *(u32x4*)(xb + ro + bj * 128) = o; } }
	v_pk_fma_f32 v[84:85], v[84:85], v[90:91], v[192:193] op_sel_hi:[1,0,1]
	v_pk_fma_f32 v[82:83], v[82:83], v[90:91], v[220:221] op_sel_hi:[1,0,1]
	v_pk_fma_f32 v[86:87], v[80:81], v[90:91], v[194:195] op_sel_hi:[1,0,1]
	v_pk_fma_f32 v[80:81], v[78:79], v[90:91], v[222:223] op_sel_hi:[1,0,1]
	v_cvt_pk_bf16_f32 v78, v82, v83
	v_cvt_pk_bf16_f32 v79, v84, v85
	v_lshlrev_b32_e32 v124, 16, v134
	v_and_b32_e32 v125, 0xffff0000, v134
	v_lshlrev_b32_e32 v108, 16, v135
	v_and_b32_e32 v109, 0xffff0000, v135
	v_cvt_pk_bf16_f32 v80, v80, v81
	v_cvt_pk_bf16_f32 v81, v86, v87
	global_store_dwordx4 v[158:159], v[78:81], off
	v_pk_fma_f32 v[76:77], v[76:77], v[90:91], v[108:109] op_sel_hi:[1,0,1]
	v_pk_fma_f32 v[74:75], v[74:75], v[90:91], v[124:125] op_sel_hi:[1,0,1]
	v_pk_fma_f32 v[78:79], v[72:73], v[90:91], v[92:93] op_sel_hi:[1,0,1]
	v_pk_fma_f32 v[72:73], v[70:71], v[90:91], v[110:111] op_sel_hi:[1,0,1]
	v_cvt_pk_bf16_f32 v70, v74, v75
	v_cvt_pk_bf16_f32 v71, v76, v77
	v_add_co_u32_e32 v106, vcc, s53, v4
	v_cvt_pk_bf16_f32 v72, v72, v73
	v_cvt_pk_bf16_f32 v73, v78, v79
	global_store_dwordx4 v[158:159], v[70:73], off offset:256
	s_nop 0
	v_addc_co_u32_e32 v107, vcc, 0, v5, vcc
	global_load_dwordx4 v[78:81], v[106:107], off
	global_load_dwordx4 v[82:85], v[106:107], off offset:256
	v_add_co_u32_e32 v76, vcc, s54, v4
	s_waitcnt vmcnt(1)
	v_lshlrev_b32_e32 v108, 16, v78
	v_addc_co_u32_e32 v77, vcc, 0, v5, vcc
	global_load_dwordx4 v[86:89], v[76:77], off
	global_load_dwordx4 v[90:93], v[76:77], off offset:256
	v_add_co_u32_e32 v74, vcc, s55, v4
	v_and_b32_e32 v109, 0xffff0000, v78
	s_nop 0
	v_addc_co_u32_e32 v75, vcc, 0, v5, vcc
	global_load_dwordx4 v[94:97], v[74:75], off
	global_load_dwordx4 v[98:101], v[74:75], off offset:256
	v_add_co_u32_e32 v4, vcc, s56, v4
	v_lshlrev_b32_e32 v78, 16, v79
	s_nop 0
	v_addc_co_u32_e32 v5, vcc, 0, v5, vcc
	global_load_dwordx4 v[102:105], v[4:5], off
	global_load_dwordx4 v[70:73], v[4:5], off offset:256
	ds_read_b32 v134, v3 offset:1028
	v_and_b32_e32 v79, 0xffff0000, v79
	v_lshlrev_b32_e32 v110, 16, v80
	v_and_b32_e32 v111, 0xffff0000, v80
	v_lshlrev_b32_e32 v80, 16, v81
	v_and_b32_e32 v81, 0xffff0000, v81
	s_waitcnt vmcnt(6)
	v_lshlrev_b32_e32 v112, 16, v82
	v_and_b32_e32 v113, 0xffff0000, v82
	v_lshlrev_b32_e32 v114, 16, v84
	v_and_b32_e32 v115, 0xffff0000, v84
	v_lshlrev_b32_e32 v84, 16, v85
	v_and_b32_e32 v85, 0xffff0000, v85
	s_waitcnt lgkmcnt(0)
	v_pk_fma_f32 v[68:69], v[68:69], v[134:135], v[78:79] op_sel_hi:[1,0,1]
	v_pk_fma_f32 v[66:67], v[66:67], v[134:135], v[108:109] op_sel_hi:[1,0,1]
	v_pk_fma_f32 v[78:79], v[64:65], v[134:135], v[80:81] op_sel_hi:[1,0,1]
	v_pk_fma_f32 v[64:65], v[62:63], v[134:135], v[110:111] op_sel_hi:[1,0,1]
	v_cvt_pk_bf16_f32 v62, v66, v67
	v_cvt_pk_bf16_f32 v63, v68, v69
	v_lshlrev_b32_e32 v82, 16, v83
	v_and_b32_e32 v83, 0xffff0000, v83
	v_cvt_pk_bf16_f32 v64, v64, v65
	v_cvt_pk_bf16_f32 v65, v78, v79
	global_store_dwordx4 v[106:107], v[62:65], off
	v_pk_fma_f32 v[58:59], v[58:59], v[134:135], v[112:113] op_sel_hi:[1,0,1]
	v_pk_fma_f32 v[60:61], v[60:61], v[134:135], v[82:83] op_sel_hi:[1,0,1]
	v_pk_fma_f32 v[62:63], v[56:57], v[134:135], v[84:85] op_sel_hi:[1,0,1]
	v_pk_fma_f32 v[56:57], v[54:55], v[134:135], v[114:115] op_sel_hi:[1,0,1]
	v_cvt_pk_bf16_f32 v54, v58, v59
	v_cvt_pk_bf16_f32 v55, v60, v61
	s_andn2_b64 vcc, exec, s[6:7]
	v_cvt_pk_bf16_f32 v56, v56, v57
	v_cvt_pk_bf16_f32 v57, v62, v63
	ds_read_b32 v58, v3 offset:1156
	global_store_dwordx4 v[106:107], v[54:57], off offset:256
	s_waitcnt vmcnt(7)
	v_lshlrev_b32_e32 v116, 16, v86
	v_and_b32_e32 v117, 0xffff0000, v86
	v_lshlrev_b32_e32 v86, 16, v87
	v_and_b32_e32 v87, 0xffff0000, v87
	v_lshlrev_b32_e32 v118, 16, v88
	v_and_b32_e32 v119, 0xffff0000, v88
	v_lshlrev_b32_e32 v88, 16, v89
	v_and_b32_e32 v89, 0xffff0000, v89
	s_waitcnt vmcnt(6)
	v_lshlrev_b32_e32 v120, 16, v90
	v_and_b32_e32 v121, 0xffff0000, v90
	v_lshlrev_b32_e32 v122, 16, v92
	v_and_b32_e32 v123, 0xffff0000, v92
	v_lshlrev_b32_e32 v92, 16, v93
	v_and_b32_e32 v93, 0xffff0000, v93
	s_waitcnt lgkmcnt(0)
; __device__ __forceinline__ unsigned cvt_pk_bf16(float lo, float hi) { unsigned r; asm volatile("v_cvt_pk_bf16_f32 %0, %1, %2" : "=v"(r) : "v"(lo), "v"(hi)); return r; }
;     __device__ __forceinline__ void operator()(const pg8::f32x4 (&acc)[2][2][4][2], const pg8::Unit& u, int ui, int wr, int wc, int fr, int fq) const {
;     ...
; #pragma unroll
;             for (int m = 0; m < 4; ++m) { const size_t ro = off0 + (size_t)(ai * 128 + m * 16) * D; const float rB = tb[(ai * 128 + m * 16) * 2];
; #pragma unroll
;                 for (int bj = 0; bj < 2; ++bj) {
;                     const pg8::f32x4 y0 = x[m][bj][0] + acc[ai][bj][m][0] * rB, y1 = x[m][bj][1] + acc[ai][bj][m][1] * rB;
;                     u32x4 o; o.x = pg8::cvt_pk_bf16(y0[0], y0[1]); o.y = pg8::cvt_pk_bf16(y0[2], y0[3]); o.z = pg8::cvt_pk_bf16(y1[0], y1[1]); o.w = pg8::cvt_pk_bf16(y1[2], y1[3]);
;                     *(u32x4*)(xb + ro + bj * 128) = o; } }
	v_pk_fma_f32 v[52:53], v[52:53], v[58:59], v[86:87] op_sel_hi:[1,0,1]
	v_pk_fma_f32 v[50:51], v[50:51], v[58:59], v[116:117] op_sel_hi:[1,0,1]
	v_pk_fma_f32 v[54:55], v[48:49], v[58:59], v[88:89] op_sel_hi:[1,0,1]
	v_pk_fma_f32 v[48:49], v[46:47], v[58:59], v[118:119] op_sel_hi:[1,0,1]
	v_cvt_pk_bf16_f32 v46, v50, v51
	v_cvt_pk_bf16_f32 v47, v52, v53
	v_lshlrev_b32_e32 v90, 16, v91
	v_and_b32_e32 v91, 0xffff0000, v91
	v_cvt_pk_bf16_f32 v48, v48, v49
	v_cvt_pk_bf16_f32 v49, v54, v55
	global_store_dwordx4 v[76:77], v[46:49], off
	v_pk_fma_f32 v[42:43], v[42:43], v[58:59], v[120:121] op_sel_hi:[1,0,1]
	v_pk_fma_f32 v[44:45], v[44:45], v[58:59], v[90:91] op_sel_hi:[1,0,1]
	v_pk_fma_f32 v[46:47], v[40:41], v[58:59], v[92:93] op_sel_hi:[1,0,1]
	v_pk_fma_f32 v[40:41], v[38:39], v[58:59], v[122:123] op_sel_hi:[1,0,1]
	v_cvt_pk_bf16_f32 v38, v42, v43
	v_cvt_pk_bf16_f32 v39, v44, v45
	s_waitcnt vmcnt(6)
	v_lshlrev_b32_e32 v124, 16, v94
	v_cvt_pk_bf16_f32 v40, v40, v41
	v_cvt_pk_bf16_f32 v41, v46, v47
	ds_read_b32 v42, v3 offset:1284
	v_and_b32_e32 v125, 0xffff0000, v94
	v_lshlrev_b32_e32 v94, 16, v95
	v_and_b32_e32 v95, 0xffff0000, v95
	v_lshlrev_b32_e32 v126, 16, v96
	v_and_b32_e32 v127, 0xffff0000, v96
	v_lshlrev_b32_e32 v96, 16, v97
	v_and_b32_e32 v97, 0xffff0000, v97
	s_waitcnt vmcnt(5)
	v_lshlrev_b32_e32 v128, 16, v98
	v_and_b32_e32 v129, 0xffff0000, v98
	v_lshlrev_b32_e32 v130, 16, v100
	v_and_b32_e32 v131, 0xffff0000, v100
	v_lshlrev_b32_e32 v100, 16, v101
	v_and_b32_e32 v101, 0xffff0000, v101
	global_store_dwordx4 v[76:77], v[38:41], off offset:256
	s_waitcnt lgkmcnt(0)
	v_pk_fma_f32 v[36:37], v[36:37], v[42:43], v[94:95] op_sel_hi:[1,0,1]
	v_pk_fma_f32 v[34:35], v[34:35], v[42:43], v[124:125] op_sel_hi:[1,0,1]
	v_pk_fma_f32 v[38:39], v[32:33], v[42:43], v[96:97] op_sel_hi:[1,0,1]
	v_pk_fma_f32 v[32:33], v[30:31], v[42:43], v[126:127] op_sel_hi:[1,0,1]
	v_cvt_pk_bf16_f32 v30, v34, v35
	v_cvt_pk_bf16_f32 v31, v36, v37
	v_lshlrev_b32_e32 v98, 16, v99
	v_and_b32_e32 v99, 0xffff0000, v99
	v_cvt_pk_bf16_f32 v32, v32, v33
	v_cvt_pk_bf16_f32 v33, v38, v39
	global_store_dwordx4 v[74:75], v[30:33], off
	v_pk_fma_f32 v[26:27], v[26:27], v[42:43], v[128:129] op_sel_hi:[1,0,1]
	v_pk_fma_f32 v[28:29], v[28:29], v[42:43], v[98:99] op_sel_hi:[1,0,1]
	v_pk_fma_f32 v[30:31], v[24:25], v[42:43], v[100:101] op_sel_hi:[1,0,1]
	v_pk_fma_f32 v[24:25], v[22:23], v[42:43], v[130:131] op_sel_hi:[1,0,1]
	v_cvt_pk_bf16_f32 v22, v26, v27
	v_cvt_pk_bf16_f32 v23, v28, v29
	s_waitcnt vmcnt(6)
	v_lshlrev_b32_e32 v132, 16, v102
	v_cvt_pk_bf16_f32 v24, v24, v25
	v_cvt_pk_bf16_f32 v25, v30, v31
	ds_read_b32 v26, v3 offset:1412
	v_and_b32_e32 v133, 0xffff0000, v102
	v_lshlrev_b32_e32 v102, 16, v103
	v_and_b32_e32 v103, 0xffff0000, v103
	v_lshlrev_b32_e32 v136, 16, v104
	v_and_b32_e32 v137, 0xffff0000, v104
	v_lshlrev_b32_e32 v104, 16, v105
	v_and_b32_e32 v105, 0xffff0000, v105
	s_waitcnt vmcnt(5)
	v_lshlrev_b32_e32 v46, 16, v72
	v_and_b32_e32 v47, 0xffff0000, v72
	v_lshlrev_b32_e32 v28, 16, v73
	v_and_b32_e32 v29, 0xffff0000, v73
	global_store_dwordx4 v[74:75], v[22:25], off offset:256
	s_waitcnt lgkmcnt(0)
	v_pk_fma_f32 v[20:21], v[20:21], v[26:27], v[102:103] op_sel_hi:[1,0,1]
	v_pk_fma_f32 v[18:19], v[18:19], v[26:27], v[132:133] op_sel_hi:[1,0,1]
	v_pk_fma_f32 v[22:23], v[16:17], v[26:27], v[104:105] op_sel_hi:[1,0,1]
	v_pk_fma_f32 v[16:17], v[14:15], v[26:27], v[136:137] op_sel_hi:[1,0,1]
	v_cvt_pk_bf16_f32 v14, v18, v19
	v_cvt_pk_bf16_f32 v15, v20, v21
	v_lshlrev_b32_e32 v60, 16, v70
	v_and_b32_e32 v61, 0xffff0000, v70
	v_lshlrev_b32_e32 v44, 16, v71
	v_and_b32_e32 v45, 0xffff0000, v71
	v_cvt_pk_bf16_f32 v16, v16, v17
	v_cvt_pk_bf16_f32 v17, v22, v23
	global_store_dwordx4 v[4:5], v[14:17], off
	v_pk_fma_f32 v[12:13], v[12:13], v[26:27], v[44:45] op_sel_hi:[1,0,1]
	v_pk_fma_f32 v[10:11], v[10:11], v[26:27], v[60:61] op_sel_hi:[1,0,1]
	v_pk_fma_f32 v[14:15], v[8:9], v[26:27], v[28:29] op_sel_hi:[1,0,1]
	v_pk_fma_f32 v[8:9], v[6:7], v[26:27], v[46:47] op_sel_hi:[1,0,1]
	v_cvt_pk_bf16_f32 v6, v10, v11
	v_cvt_pk_bf16_f32 v7, v12, v13
	s_nop 0
	v_cvt_pk_bf16_f32 v8, v8, v9
	v_cvt_pk_bf16_f32 v9, v14, v15
	global_store_dwordx4 v[4:5], v[6:9], off offset:256
	s_cbranch_vccnz .LBB0_1294
	s_andn2_b64 vcc, exec, s[12:13]
	s_cbranch_vccnz .LBB0_1293
	s_barrier
	s_branch .LBB0_1293
